# GDN recurrence hand-rescheduled with K=32 bf16 MFMAs (same numerics kind), HGRN q4 loop unrolled + LDS double buffer, MLP-down GEMMs: 4-way split-K tail with f32 partials (both layers)
# speedup vs baseline: 1.0384x; 1.0384x over previous
.LBB0_409:
	v_mul_u32_u24_e32 v0, 0x110, v206
	v_add_u32_e32 v0, v0, v209
	v_add_u32_e32 v3, 0x16000, v0
	v_add_u32_e32 v187, v208, v213
	v_add_u32_e32 v187, 0x1a400, v187
	v_xor_b32_e32 v214, v207, v210
	v_lshl_add_u32 v215, v214, 3, v213
	v_xor_b32_e32 v214, 2, v214
	v_add_u32_e32 v215, 0xd000, v215
	v_lshl_add_u32 v214, v214, 3, v213
	v_add_u32_e32 v214, 0xd000, v214
	v_and_b32_e32 v208, 48, v205
	v_add_u32_e32 v208, s83, v208
	v_add3_u32 v209, s87, v212, v211
	ds_read_b64 v[140:141], v3 offset:0
	ds_read_b64 v[142:143], v3 offset:32
	ds_read_b64 v[144:145], v0 offset:0
	ds_read_b64 v[146:147], v0 offset:32
	ds_read_b64 v[148:149], v3 offset:64
	ds_read_b64 v[150:151], v3 offset:96
	ds_read_b64 v[152:153], v0 offset:64
	ds_read_b64 v[154:155], v0 offset:96
	ds_read_b128 v[164:167], v208 offset:0
	ds_read_b64 v[156:157], v3 offset:128
	ds_read_b64 v[158:159], v3 offset:160
	ds_read_b64 v[160:161], v0 offset:128
	ds_read_b64 v[162:163], v0 offset:160
	v_cvt_pk_bf16_f32 v228, v20, v21
	v_cvt_pk_bf16_f32 v229, v22, v23
	v_cvt_pk_bf16_f32 v230, v4, v5
	v_cvt_pk_bf16_f32 v231, v6, v7
	v_cvt_pk_bf16_f32 v232, v32, v33
	v_cvt_pk_bf16_f32 v233, v34, v35
	v_cvt_pk_bf16_f32 v234, v16, v17
	v_cvt_pk_bf16_f32 v235, v18, v19
	v_cvt_pk_bf16_f32 v236, v28, v29
	v_cvt_pk_bf16_f32 v237, v30, v31
	v_cvt_pk_bf16_f32 v238, v12, v13
	v_cvt_pk_bf16_f32 v239, v14, v15
	v_cvt_pk_bf16_f32 v240, v24, v25
	v_cvt_pk_bf16_f32 v241, v26, v27
	v_cvt_pk_bf16_f32 v242, v8, v9
	v_cvt_pk_bf16_f32 v243, v10, v11
	v_mul_f32_e32 v169, s63, v201
	v_exp_f32_e32 v168, v169
	s_waitcnt lgkmcnt(9)
	v_mfma_f32_16x16x32_bf16 v[116:119], v[140:143], v[228:231], v[116:119]
	v_mfma_f32_16x16x32_bf16 v[124:127], v[144:147], v[228:231], 0
	ds_read_b64 v[140:141], v3 offset:192
	ds_read_b64 v[142:143], v3 offset:224
	ds_read_b64 v[144:145], v0 offset:192
	ds_read_b64 v[146:147], v0 offset:224
	v_pk_mul_f32 v[20:21], v[20:21], v[168:169] op_sel_hi:[1,0]
	v_pk_mul_f32 v[22:23], v[22:23], v[168:169] op_sel_hi:[1,0]
	s_waitcnt lgkmcnt(9)
	v_mfma_f32_16x16x32_bf16 v[116:119], v[148:151], v[232:235], v[116:119]
	v_mfma_f32_16x16x32_bf16 v[124:127], v[152:155], v[232:235], v[124:127]
	ds_read_b64 v[148:149], v3 offset:4352
	ds_read_b64 v[150:151], v3 offset:4384
	ds_read_b64 v[152:153], v0 offset:4352
	ds_read_b64 v[154:155], v0 offset:4384
	v_pk_mul_f32 v[4:5], v[4:5], v[168:169] op_sel_hi:[1,0]
	v_pk_mul_f32 v[6:7], v[6:7], v[168:169] op_sel_hi:[1,0]
	s_waitcnt lgkmcnt(8)
	v_mfma_f32_16x16x32_bf16 v[116:119], v[156:159], v[236:239], v[116:119]
	v_mfma_f32_16x16x32_bf16 v[124:127], v[160:163], v[236:239], v[124:127]
	ds_read_b64 v[156:157], v3 offset:4416
	ds_read_b64 v[158:159], v3 offset:4448
	ds_read_b64 v[160:161], v0 offset:4416
	ds_read_b64 v[162:163], v0 offset:4448
	v_pk_mul_f32 v[32:33], v[32:33], v[168:169] op_sel_hi:[1,0]
	v_pk_mul_f32 v[34:35], v[34:35], v[168:169] op_sel_hi:[1,0]
	s_waitcnt lgkmcnt(8)
	v_mfma_f32_16x16x32_bf16 v[116:119], v[140:143], v[240:243], v[116:119]
	v_mfma_f32_16x16x32_bf16 v[124:127], v[144:147], v[240:243], v[124:127]
	ds_read_b64 v[140:141], v3 offset:4480
	ds_read_b64 v[142:143], v3 offset:4512
	ds_read_b64 v[144:145], v0 offset:4480
	ds_read_b64 v[146:147], v0 offset:4512
	ds_read_b128 v[252:255], v208 offset:64
	v_pk_mul_f32 v[16:17], v[16:17], v[168:169] op_sel_hi:[1,0]
	v_pk_mul_f32 v[18:19], v[18:19], v[168:169] op_sel_hi:[1,0]
	s_waitcnt lgkmcnt(9)
	v_mfma_f32_16x16x32_bf16 v[108:111], v[148:151], v[228:231], v[108:111]
	v_mfma_f32_16x16x32_bf16 v[128:131], v[152:155], v[228:231], 0
	ds_read_b64 v[148:149], v3 offset:4544
	ds_read_b64 v[150:151], v3 offset:4576
	ds_read_b64 v[152:153], v0 offset:4544
	ds_read_b64 v[154:155], v0 offset:4576
	v_pk_mul_f32 v[28:29], v[28:29], v[168:169] op_sel_hi:[1,0]
	v_pk_mul_f32 v[30:31], v[30:31], v[168:169] op_sel_hi:[1,0]
	s_waitcnt lgkmcnt(9)
	v_mfma_f32_16x16x32_bf16 v[108:111], v[156:159], v[232:235], v[108:111]
	v_mfma_f32_16x16x32_bf16 v[128:131], v[160:163], v[232:235], v[128:131]
	ds_read_b64 v[156:157], v3 offset:8704
	ds_read_b64 v[158:159], v3 offset:8736
	ds_read_b64 v[160:161], v0 offset:8704
	ds_read_b64 v[162:163], v0 offset:8736
	v_pk_mul_f32 v[12:13], v[12:13], v[168:169] op_sel_hi:[1,0]
	v_pk_mul_f32 v[14:15], v[14:15], v[168:169] op_sel_hi:[1,0]
	v_pk_mul_f32 v[124:125], v[124:125], v[164:165]
	v_pk_mul_f32 v[126:127], v[126:127], v[166:167]
	v_cvt_pk_bf16_f32 v244, v116, v117
	v_cvt_pk_bf16_f32 v245, v118, v119
	s_waitcnt lgkmcnt(9)
	v_mfma_f32_16x16x32_bf16 v[108:111], v[140:143], v[236:239], v[108:111]
	v_mfma_f32_16x16x32_bf16 v[128:131], v[144:147], v[236:239], v[128:131]
	ds_read_b64 v[140:141], v3 offset:8768
	ds_read_b64 v[142:143], v3 offset:8800
	ds_read_b64 v[144:145], v0 offset:8768
	ds_read_b64 v[146:147], v0 offset:8800
	v_pk_mul_f32 v[24:25], v[24:25], v[168:169] op_sel_hi:[1,0]
	v_pk_mul_f32 v[26:27], v[26:27], v[168:169] op_sel_hi:[1,0]
	s_waitcnt lgkmcnt(8)
	v_mfma_f32_16x16x32_bf16 v[108:111], v[148:151], v[240:243], v[108:111]
	v_mfma_f32_16x16x32_bf16 v[128:131], v[152:155], v[240:243], v[128:131]
	ds_read_b64 v[148:149], v3 offset:8832
	ds_read_b64 v[150:151], v3 offset:8864
	ds_read_b64 v[152:153], v0 offset:8832
	ds_read_b64 v[154:155], v0 offset:8864
	ds_read_b128 v[164:167], v208 offset:128
	v_pk_mul_f32 v[8:9], v[8:9], v[168:169] op_sel_hi:[1,0]
	v_pk_mul_f32 v[10:11], v[10:11], v[168:169] op_sel_hi:[1,0]
	s_waitcnt lgkmcnt(9)
	v_mfma_f32_16x16x32_bf16 v[120:123], v[156:159], v[228:231], v[120:123]
	v_mfma_f32_16x16x32_bf16 v[132:135], v[160:163], v[228:231], 0
	ds_read_b64 v[156:157], v3 offset:8896
	ds_read_b64 v[158:159], v3 offset:8928
	ds_read_b64 v[160:161], v0 offset:8896
	ds_read_b64 v[162:163], v0 offset:8928
	s_waitcnt lgkmcnt(9)
	v_mfma_f32_16x16x32_bf16 v[120:123], v[140:143], v[232:235], v[120:123]
	v_mfma_f32_16x16x32_bf16 v[132:135], v[144:147], v[232:235], v[132:135]
	ds_read_b64 v[140:141], v3 offset:13056
	ds_read_b64 v[142:143], v3 offset:13088
	ds_read_b64 v[144:145], v0 offset:13056
	ds_read_b64 v[146:147], v0 offset:13088
	v_pk_mul_f32 v[128:129], v[128:129], v[252:253]
	v_pk_mul_f32 v[130:131], v[130:131], v[254:255]
	v_cvt_pk_bf16_f32 v246, v108, v109
	v_cvt_pk_bf16_f32 v247, v110, v111
	s_waitcnt lgkmcnt(9)
	v_mfma_f32_16x16x32_bf16 v[120:123], v[148:151], v[236:239], v[120:123]
	v_mfma_f32_16x16x32_bf16 v[132:135], v[152:155], v[236:239], v[132:135]
	ds_read_b64 v[148:149], v3 offset:13120
	ds_read_b64 v[150:151], v3 offset:13152
	ds_read_b64 v[152:153], v0 offset:13120
	ds_read_b64 v[154:155], v0 offset:13152
	s_waitcnt lgkmcnt(8)
	v_mfma_f32_16x16x32_bf16 v[120:123], v[156:159], v[240:243], v[120:123]
	v_mfma_f32_16x16x32_bf16 v[132:135], v[160:163], v[240:243], v[132:135]
	ds_read_b64 v[156:157], v3 offset:13184
	ds_read_b64 v[158:159], v3 offset:13216
	ds_read_b64 v[160:161], v0 offset:13184
	ds_read_b64 v[162:163], v0 offset:13216
	ds_read_b128 v[252:255], v208 offset:192
	s_waitcnt lgkmcnt(9)
	v_mfma_f32_16x16x32_bf16 v[112:115], v[140:143], v[228:231], v[112:115]
	v_mfma_f32_16x16x32_bf16 v[136:139], v[144:147], v[228:231], 0
	ds_read_b64 v[140:141], v3 offset:13248
	ds_read_b64 v[142:143], v3 offset:13280
	ds_read_b64 v[144:145], v0 offset:13248
	ds_read_b64 v[146:147], v0 offset:13280
	s_waitcnt lgkmcnt(9)
	v_mfma_f32_16x16x32_bf16 v[112:115], v[148:151], v[232:235], v[112:115]
	v_mfma_f32_16x16x32_bf16 v[136:139], v[152:155], v[232:235], v[136:139]
	v_pk_mul_f32 v[132:133], v[132:133], v[164:165]
	v_pk_mul_f32 v[134:135], v[134:135], v[166:167]
	v_cvt_pk_bf16_f32 v248, v120, v121
	v_cvt_pk_bf16_f32 v249, v122, v123
	s_waitcnt lgkmcnt(5)
	v_mfma_f32_16x16x32_bf16 v[112:115], v[156:159], v[236:239], v[112:115]
	v_mfma_f32_16x16x32_bf16 v[136:139], v[160:163], v[236:239], v[136:139]
	s_waitcnt lgkmcnt(0)
	v_mfma_f32_16x16x32_bf16 v[112:115], v[140:143], v[240:243], v[112:115]
	v_mfma_f32_16x16x32_bf16 v[136:139], v[144:147], v[240:243], v[136:139]
	ds_read_b64 v[140:141], v187 offset:0
	ds_read_b64 v[144:145], v187 offset:2304
	ds_read_b64 v[146:147], v187 offset:2336
	ds_read_b64 v[148:149], v187 offset:4608
	ds_read_b64 v[150:151], v187 offset:4640
	ds_read_b64 v[142:143], v187 offset:4672
	ds_read_b64 v[152:153], v187 offset:6912
	ds_read_b64 v[154:155], v187 offset:6944
	ds_read_b64 v[156:157], v187 offset:6976
	ds_read_b64 v[158:159], v187 offset:7008
	s_nop 1
	v_pk_mul_f32 v[136:137], v[136:137], v[252:253]
	v_pk_mul_f32 v[138:139], v[138:139], v[254:255]
	v_cvt_pk_bf16_f32 v250, v112, v113
	v_cvt_pk_bf16_f32 v251, v114, v115
	s_waitcnt lgkmcnt(9)
	v_mfma_f32_16x16x16_bf16 v[124:127], v[140:141], v[244:245], v[124:127]
	s_waitcnt lgkmcnt(7)
	v_mfma_f32_16x16x32_bf16 v[128:131], v[144:147], v[244:247], v[128:131]
	s_waitcnt lgkmcnt(5)
	v_mfma_f32_16x16x32_bf16 v[132:135], v[148:151], v[244:247], v[132:135]
	s_waitcnt lgkmcnt(2)
	v_mfma_f32_16x16x32_bf16 v[136:139], v[152:155], v[244:247], v[136:139]
	v_mfma_f32_16x16x16_bf16 v[132:135], v[142:143], v[248:249], v[132:135]
	s_waitcnt lgkmcnt(0)
	v_mfma_f32_16x16x32_bf16 v[136:139], v[156:159], v[248:251], v[136:139]
	ds_read_b64 v[116:117], v215 offset:0
	ds_read_b64 v[118:119], v215 offset:32
	ds_read_b64 v[108:109], v215 offset:64
	ds_read_b64 v[110:111], v215 offset:96
	ds_read_b64 v[120:121], v214 offset:2304
	ds_read_b64 v[122:123], v214 offset:2336
	ds_read_b64 v[112:113], v214 offset:2368
	ds_read_b64 v[114:115], v214 offset:2400
	s_waitcnt lgkmcnt(4)
	v_mfma_f32_16x16x32_bf16 v[20:23], v[116:119], v[244:247], v[20:23]
	v_mfma_f32_16x16x32_bf16 v[20:23], v[108:111], v[248:251], v[20:23]
	ds_read_b64 v[140:141], v215 offset:4640
	ds_read_b64 v[142:143], v215 offset:4608
	ds_read_b64 v[144:145], v215 offset:4704
	ds_read_b64 v[146:147], v215 offset:4672
	s_waitcnt lgkmcnt(4)
	v_mfma_f32_16x16x32_bf16 v[4:7], v[120:123], v[244:247], v[4:7]
	v_mfma_f32_16x16x32_bf16 v[4:7], v[112:115], v[248:251], v[4:7]
	ds_read_b64 v[148:149], v214 offset:6944
	ds_read_b64 v[150:151], v214 offset:6912
	ds_read_b64 v[152:153], v214 offset:7008
	ds_read_b64 v[154:155], v214 offset:6976
	v_cvt_pk_bf16_f32 v170, v124, s0
	ds_write_b16 v209, v170 offset:0
	v_cvt_pk_bf16_f32 v170, v125, s0
	ds_write_b16 v209, v170 offset:272
	v_cvt_pk_bf16_f32 v170, v126, s0
	ds_write_b16 v209, v170 offset:544
	v_cvt_pk_bf16_f32 v170, v127, s0
	ds_write_b16 v209, v170 offset:816
	s_waitcnt lgkmcnt(8)
	v_mfma_f32_16x16x32_bf16 v[32:35], v[140:143], v[244:247], v[32:35]
	v_mfma_f32_16x16x32_bf16 v[32:35], v[144:147], v[248:251], v[32:35]
	ds_read_b64 v[116:117], v215 offset:9280
	ds_read_b64 v[118:119], v215 offset:9312
	ds_read_b64 v[108:109], v215 offset:9216
	ds_read_b64 v[110:111], v215 offset:9248
	v_cvt_pk_bf16_f32 v170, v128, s0
	ds_write_b16 v209, v170 offset:4352
	v_cvt_pk_bf16_f32 v170, v129, s0
	ds_write_b16 v209, v170 offset:4624
	v_cvt_pk_bf16_f32 v170, v130, s0
	ds_write_b16 v209, v170 offset:4896
	v_cvt_pk_bf16_f32 v170, v131, s0
	ds_write_b16 v209, v170 offset:5168
	s_waitcnt lgkmcnt(12)
	v_mfma_f32_16x16x32_bf16 v[16:19], v[148:151], v[244:247], v[16:19]
	v_mfma_f32_16x16x32_bf16 v[16:19], v[152:155], v[248:251], v[16:19]
	ds_read_b64 v[120:121], v214 offset:11584
	ds_read_b64 v[122:123], v214 offset:11616
	ds_read_b64 v[112:113], v214 offset:11520
	ds_read_b64 v[114:115], v214 offset:11552
	v_cvt_pk_bf16_f32 v170, v132, s0
	ds_write_b16 v209, v170 offset:8704
	v_cvt_pk_bf16_f32 v170, v133, s0
	ds_write_b16 v209, v170 offset:8976
	v_cvt_pk_bf16_f32 v170, v134, s0
	ds_write_b16 v209, v170 offset:9248
	v_cvt_pk_bf16_f32 v170, v135, s0
	ds_write_b16 v209, v170 offset:9520
	s_waitcnt lgkmcnt(12)
	v_mfma_f32_16x16x32_bf16 v[28:31], v[116:119], v[244:247], v[28:31]
	v_mfma_f32_16x16x32_bf16 v[28:31], v[108:111], v[248:251], v[28:31]
	ds_read_b64 v[140:141], v215 offset:13920
	ds_read_b64 v[142:143], v215 offset:13888
	ds_read_b64 v[144:145], v215 offset:13856
	ds_read_b64 v[146:147], v215 offset:13824
	v_cvt_pk_bf16_f32 v170, v136, s0
	ds_write_b16 v209, v170 offset:13056
	v_cvt_pk_bf16_f32 v170, v137, s0
	ds_write_b16 v209, v170 offset:13328
	v_cvt_pk_bf16_f32 v170, v138, s0
	ds_write_b16 v209, v170 offset:13600
	v_cvt_pk_bf16_f32 v170, v139, s0
	ds_write_b16 v209, v170 offset:13872
	s_waitcnt lgkmcnt(12)
	v_mfma_f32_16x16x32_bf16 v[12:15], v[120:123], v[244:247], v[12:15]
	v_mfma_f32_16x16x32_bf16 v[12:15], v[112:115], v[248:251], v[12:15]
	ds_read_b64 v[148:149], v214 offset:16224
	ds_read_b64 v[150:151], v214 offset:16192
	ds_read_b64 v[152:153], v214 offset:16160
	ds_read_b64 v[154:155], v214 offset:16128
	s_waitcnt lgkmcnt(8)
	v_mfma_f32_16x16x32_bf16 v[24:27], v[140:143], v[244:247], v[24:27]
	v_mfma_f32_16x16x32_bf16 v[24:27], v[144:147], v[248:251], v[24:27]
	s_waitcnt lgkmcnt(0)
	v_mfma_f32_16x16x32_bf16 v[8:11], v[148:151], v[244:247], v[8:11]
	v_mfma_f32_16x16x32_bf16 v[8:11], v[152:155], v[248:251], v[8:11]
	v_lshl_add_u32 v0, s94, 6, v173
	v_xad_u32 v3, v0, -1, s80
	v_cndmask_b32_e64 v3, v3, v0, s[4:5]
	v_lshlrev_b32_e32 v0, 5, v205
	v_mul_lo_u32 v116, v173, s71
	v_and_b32_e32 v0, 0xe0, v0
	s_waitcnt lgkmcnt(0)
	s_barrier
	v_add3_u32 v118, s12, v116, v0
	ds_read_b128 v[114:117], v118
	ds_read_b128 v[118:121], v118 offset:16
	v_add_u32_e32 v122, v3, v177
	v_ashrrev_i32_e32 v123, 31, v122
	v_lshlrev_b64 v[112:113], 11, v[122:123]
	v_lshl_add_u64 v[112:113], v[184:185], 0, v[112:113]
	v_lshl_add_u64 v[110:111], v[112:113], 0, v[0:1]
	s_waitcnt lgkmcnt(1)
	global_store_dwordx4 v[110:111], v[114:117], off
	s_waitcnt lgkmcnt(0)
	global_store_dwordx4 v[110:111], v[118:121], off offset:16
	s_cmp_eq_u32 s13, s85
	s_cbranch_scc1 .LBB0_411
	s_mov_b32 s94, s13
	s_branch .LBB0_355

.LBB0_738:
	s_or_b64 exec, exec, s[4:5]
	s_mov_b64 s[8:9], s[0:1]
	s_waitcnt lgkmcnt(0)
	v_mov_b32_e32 v0, v188
	s_barrier
	s_add_i32 s4, 0, 0x24ffc
	v_mov_b32_e32 v0, s4
	ds_read_b32 v0, v0
	s_movk_i32 s4, 0x13f
	v_mov_b32_e32 v8, v188
	s_waitcnt lgkmcnt(0)
	v_cmp_lt_i32_e32 vcc, s4, v0
	v_readfirstlane_b32 s27, v0
	v_readfirstlane_b32 s16, v8
	s_cbranch_vccnz .LBB0_754
	v_lshlrev_b32_e32 v0, 4, v8
	v_add_u32_e32 v1, 0x2000, v0
	v_ashrrev_i32_e32 v2, 31, v1
	v_lshrrev_b32_e32 v2, 22, v2
	v_add_u32_e32 v2, v1, v2
	v_ashrrev_i32_e32 v9, 10, v2
	v_mul_i32_i24_e32 v2, 0x400, v9
	v_sub_u32_e32 v1, v1, v2
	v_lshrrev_b32_e32 v2, 4, v1
	v_bitop3_b32 v1, v2, v1, 32 bitop3:0x6c
	v_ashrrev_i32_e32 v2, 31, v1
	v_lshrrev_b32_e32 v2, 26, v2
	v_add_u32_e32 v2, v1, v2
	v_lshlrev_b32_e32 v3, 3, v9
	v_ashrrev_i32_e32 v10, 6, v2
	v_and_b32_e32 v3, -16, v3
	v_add_u32_e32 v3, v10, v3
	s_load_dwordx4 s[4:7], s[8:9], 0xa8
	v_and_b32_e32 v4, 3, v10
	s_mov_b32 s8, 0x7ffe0
	v_lshrrev_b32_e32 v5, 2, v3
	v_lshlrev_b32_e32 v6, 1, v3
	v_and_b32_e32 v2, 0xc0, v2
	v_and_or_b32 v4, v3, s8, v4
	v_and_b32_e32 v5, 4, v5
	v_and_b32_e32 v6, 24, v6
	v_sub_u32_e32 v1, v1, v2
	v_mov_b32_e32 v2, 1
	v_or3_b32 v4, v4, v5, v6
	v_lshlrev_b32_e32 v5, 5, v9
	v_ashrrev_i16_sdwa v1, v2, sext(v1) dst_sel:DWORD dst_unused:UNUSED_PAD src0_sel:DWORD src1_sel:BYTE_0
	v_and_b32_e32 v5, 32, v5
	v_bfe_i32 v11, v1, 0, 16
	v_add_lshl_u32 v1, v5, v11, 1
	v_lshl_add_u32 v128, v4, 13, v1
	v_lshl_add_u32 v130, v3, 13, v1
	v_bfe_i32 v1, v8, 27, 1
	v_lshrrev_b32_e32 v1, 22, v1
	v_add_u32_e32 v1, v0, v1
	v_and_b32_e32 v1, 0xfffffc00, v1
	v_sub_u32_e32 v0, v0, v1
	v_lshrrev_b32_e32 v1, 4, v0
	v_ashrrev_i32_e32 v3, 31, v8
	v_bitop3_b32 v0, v1, v0, 32 bitop3:0x6c
	v_lshrrev_b32_e32 v3, 26, v3
	v_ashrrev_i32_e32 v1, 31, v0
	v_add_u32_e32 v3, v8, v3
	v_lshrrev_b32_e32 v1, 26, v1
	v_ashrrev_i32_e32 v13, 6, v3
	v_add_u32_e32 v1, v0, v1
	v_lshlrev_b32_e32 v3, 3, v13
	s_waitcnt lgkmcnt(0)
	s_add_u32 s56, s4, 0x6800000
	v_ashrrev_i32_e32 v12, 6, v1
	v_and_b32_e32 v3, -16, v3
	s_addc_u32 s57, s5, 0
	v_add_u32_e32 v3, v12, v3
	v_and_b32_e32 v4, 3, v12
	s_ashr_i32 s59, s27, 31
	v_and_or_b32 v4, v3, s8, v4
	s_and_b32 s8, s27, 7
	s_lshr_b32 s9, s27, 3
	s_and_b32 s98, s9, 3
	s_lshr_b32 s9, s9, 2
	s_lshl_b32 s99, s8, 3
	s_add_i32 s99, s99, s9
	s_mul_i32 s8, s8, 10
	s_cmp_eq_u32 s98, 3
	s_cbranch_scc1 .Lsk8_q3a
	s_lshr_b32 s10, s9, 2
	s_add_i32 s8, s8, s10
	s_add_i32 s8, s8, 8
	s_and_b32 s9, s9, 3
	s_lshl_b32 s10, s98, 11
	s_movk_i32 s100, 12
	s_branch .Lsk8_q3b
.Lsk8_q3a:
	s_add_i32 s8, s8, s9
	s_mov_b32 s9, 3
	s_mov_b32 s10, 0
	s_movk_i32 s100, 60
.Lsk8_q3b:
	s_lshl_b32 s8, s8, 2
	s_or_b32 s8, s8, s9
	s_mov_b32 s101, s10
	s_ashr_i32 s5, s16, 6
	s_ashr_i32 s4, s16, 8
	s_lshl_b32 s58, s5, 10
	v_lshrrev_b32_e32 v5, 2, v3
	v_lshlrev_b32_e32 v6, 1, v3
	v_and_b32_e32 v1, 0xc0, v1
	s_ashr_i32 s44, s8, 2
	v_and_b32_e32 v5, 4, v5
	v_and_b32_e32 v6, 24, v6
	v_sub_u32_e32 v0, v0, v1
	s_and_b32 s77, s8, 3
	s_ashr_i32 s45, s44, 31
	v_or3_b32 v4, v4, v5, v6
	v_lshlrev_b32_e32 v5, 5, v13
	v_ashrrev_i16_sdwa v0, v2, sext(v0) dst_sel:DWORD dst_unused:UNUSED_PAD src0_sel:DWORD src1_sel:BYTE_0
	s_lshl_b64 s[8:9], s[44:45], 21
	s_lshl_b32 s10, s77, 21
	s_add_u32 s10, s10, s101
	v_and_b32_e32 v5, 32, v5
	v_bfe_i32 v14, v0, 0, 16
	s_add_u32 s52, s56, s10
	v_add_lshl_u32 v0, v5, v14, 1
	s_addc_u32 s53, s57, 0
	s_add_i32 s45, s58, 0
	v_lshl_add_u32 v132, v4, 13, v0
	s_add_i32 m0, s45, 0x10000
	v_lshl_add_u32 v134, v3, 13, v0
	global_load_lds_dwordx4 v132, s[52:53]
	s_add_i32 m0, s45, 0x12000
	s_add_u32 s10, s52, 0x100000
	global_load_lds_dwordx4 v128, s[52:53]
	s_addc_u32 s11, s53, 0
	s_add_i32 m0, s45, 0x14000
	v_mov_b32_e32 v133, 0
	global_load_lds_dwordx4 v132, s[10:11]
	s_add_i32 m0, s45, 0x16000
	s_add_u32 s50, s6, s8
	s_addc_u32 s51, s7, s9
	s_add_u32 s50, s50, s101
	s_addc_u32 s51, s51, 0
	s_add_i32 s60, s45, 0x2000
	global_load_lds_dwordx4 v128, s[10:11]
	s_mov_b32 m0, s45
	s_add_u32 s8, s50, 0x100000
	global_load_lds_dwordx4 v134, s[50:51]
	s_mov_b32 m0, s60
	s_addc_u32 s9, s51, 0
	s_add_i32 s61, s45, 0x4000
	global_load_lds_dwordx4 v130, s[50:51]
	s_mov_b32 m0, s61
	s_add_i32 s63, s45, 0x6000
	global_load_lds_dwordx4 v134, s[8:9]
	s_mov_b32 m0, s63
	v_mov_b32_e32 v129, v133
	global_load_lds_dwordx4 v130, s[8:9]
	v_mov_b32_e32 v135, v133
	v_mov_b32_e32 v131, v133
	s_cmp_eq_u32 s4, 1
	v_lshl_add_u64 v[6:7], s[52:53], 0, v[132:133]
	v_lshl_add_u64 v[4:5], s[52:53], 0, v[128:129]
	v_lshl_add_u64 v[0:1], s[50:51], 0, v[134:135]
	s_cselect_b64 s[8:9], -1, 0
	s_cmp_lg_u32 s4, 1
	v_lshl_add_u64 v[2:3], s[50:51], 0, v[130:131]
	s_cbranch_scc1 .LBB0_741
	s_barrier

.LBB0_743:
	s_andn2_b64 vcc, exec, s[4:5]
	s_mov_b32 s77, s42
	s_mov_b32 s100, s101
	s_mov_b32 s44, s40
	s_mov_b64 s[52:53], s[48:49]
	s_mov_b64 s[50:51], s[46:47]
	s_cbranch_vccz .LBB0_753
.LBB0_744:
	s_add_i32 s68, s68, 1
	s_mov_b64 s[4:5], 0
	s_cmp_eq_u32 s98, 3
	s_cbranch_scc1 .Lsk8_h3
	s_cmp_lt_u32 s68, 3
	s_cselect_b64 s[4:5], -1, 0
	s_lshr_b32 s40, s99, 3
	s_mul_i32 s40, s40, 10
	s_and_b32 s42, s99, 7
	s_add_i32 s40, s40, s42
	s_mov_b32 s42, s98
	s_cmp_eq_u32 s68, 1
	s_cselect_b32 s54, 0x800, 0
	s_cselect_b32 s101, 44, 12
	s_branch .Lsk8_hj
.Lsk8_h3:
	s_cmp_eq_u32 s68, 1
	s_cselect_b64 s[4:5], -1, 0
	s_lshr_b32 s40, s99, 3
	s_mul_i32 s40, s40, 10
	s_bfe_u32 s42, s99, 0x10002
	s_add_i32 s40, s40, s42
	s_add_i32 s40, s40, 8
	s_and_b32 s42, s99, 3
	s_movk_i32 s54, 0x1800
	s_movk_i32 s101, 12
.Lsk8_hj:
.LBB0_746:
	s_ashr_i32 s41, s40, 31
	s_lshl_b64 s[46:47], s[40:41], 21
	s_add_u32 s46, s6, s46
	s_addc_u32 s47, s7, s47
	s_add_u32 s46, s46, s54
	s_addc_u32 s47, s47, 0
	s_and_b64 s[48:49], s[4:5], exec
	s_cselect_b32 s41, s47, s51
	s_cselect_b32 s78, s46, s50
	s_ashr_i32 s43, s42, 31
	s_lshl_b64 s[48:49], s[42:43], 21
	s_add_u32 s48, s56, s48
	s_addc_u32 s49, s57, s49
	s_add_u32 s48, s48, s54
	s_addc_u32 s49, s49, 0
	s_and_b64 s[54:55], s[4:5], exec
	s_cselect_b32 s43, s49, s53
	s_cselect_b32 s79, s48, s52
	s_add_u32 s50, s50, 0x100080
	s_addc_u32 s51, s51, 0
	s_add_u32 s80, s52, 0x100
	s_addc_u32 s81, s53, 0
	s_mov_b32 s82, -2
	s_cmp_lt_u32 s98, 3
	s_cbranch_scc0 .Lsk8_zero
	s_cmp_eq_u32 s68, 3
	s_cbranch_scc1 .LBB0_747
.Lsk8_zero:
	v_mov_b32_e32 v0, 0
	v_mov_b32_e32 v1, v0
	v_mov_b32_e32 v2, v0
	v_mov_b32_e32 v3, v0
	v_mov_b32_e32 v4, v0
	v_mov_b32_e32 v5, v0
	v_mov_b32_e32 v6, v0
	v_mov_b32_e32 v7, v0
	v_mov_b32_e32 v8, v0
	v_mov_b32_e32 v9, v0
	v_mov_b32_e32 v10, v0
	v_mov_b32_e32 v11, v0
	v_mov_b32_e32 v12, v0
	v_mov_b32_e32 v13, v0
	v_mov_b32_e32 v14, v0
	v_mov_b32_e32 v15, v0
	v_mov_b32_e32 v24, v0
	v_mov_b32_e32 v25, v0
	v_mov_b32_e32 v26, v0
	v_mov_b32_e32 v27, v0
	v_mov_b32_e32 v28, v0
	v_mov_b32_e32 v29, v0
	v_mov_b32_e32 v30, v0
	v_mov_b32_e32 v31, v0
	v_mov_b32_e32 v40, v0
	v_mov_b32_e32 v41, v0
	v_mov_b32_e32 v42, v0
	v_mov_b32_e32 v43, v0
	v_mov_b32_e32 v44, v0
	v_mov_b32_e32 v45, v0
	v_mov_b32_e32 v46, v0
	v_mov_b32_e32 v47, v0
	v_mov_b32_e32 v16, v0
	v_mov_b32_e32 v17, v0
	v_mov_b32_e32 v18, v0
	v_mov_b32_e32 v19, v0
	v_mov_b32_e32 v20, v0
	v_mov_b32_e32 v21, v0
	v_mov_b32_e32 v22, v0
	v_mov_b32_e32 v23, v0
	v_mov_b32_e32 v32, v0
	v_mov_b32_e32 v33, v0
	v_mov_b32_e32 v34, v0
	v_mov_b32_e32 v35, v0
	v_mov_b32_e32 v36, v0
	v_mov_b32_e32 v37, v0
	v_mov_b32_e32 v38, v0
	v_mov_b32_e32 v39, v0
	v_mov_b32_e32 v48, v0
	v_mov_b32_e32 v49, v0
	v_mov_b32_e32 v50, v0
	v_mov_b32_e32 v51, v0
	v_mov_b32_e32 v52, v0
	v_mov_b32_e32 v53, v0
	v_mov_b32_e32 v54, v0
	v_mov_b32_e32 v55, v0
	v_mov_b32_e32 v56, v0
	v_mov_b32_e32 v57, v0
	v_mov_b32_e32 v58, v0
	v_mov_b32_e32 v59, v0
	v_mov_b32_e32 v60, v0
	v_mov_b32_e32 v61, v0
	v_mov_b32_e32 v62, v0
	v_mov_b32_e32 v63, v0
	v_mov_b32_e32 v64, v0
	v_mov_b32_e32 v65, v0
	v_mov_b32_e32 v66, v0
	v_mov_b32_e32 v67, v0
	v_mov_b32_e32 v68, v0
	v_mov_b32_e32 v69, v0
	v_mov_b32_e32 v70, v0
	v_mov_b32_e32 v71, v0
	v_mov_b32_e32 v72, v0
	v_mov_b32_e32 v73, v0
	v_mov_b32_e32 v74, v0
	v_mov_b32_e32 v75, v0
	v_mov_b32_e32 v76, v0
	v_mov_b32_e32 v77, v0
	v_mov_b32_e32 v78, v0
	v_mov_b32_e32 v79, v0
	v_mov_b32_e32 v88, v0
	v_mov_b32_e32 v89, v0
	v_mov_b32_e32 v90, v0
	v_mov_b32_e32 v91, v0
	v_mov_b32_e32 v92, v0
	v_mov_b32_e32 v93, v0
	v_mov_b32_e32 v94, v0
	v_mov_b32_e32 v95, v0
	v_mov_b32_e32 v104, v0
	v_mov_b32_e32 v105, v0
	v_mov_b32_e32 v106, v0
	v_mov_b32_e32 v107, v0
	v_mov_b32_e32 v108, v0
	v_mov_b32_e32 v109, v0
	v_mov_b32_e32 v110, v0
	v_mov_b32_e32 v111, v0
	v_mov_b32_e32 v80, v0
	v_mov_b32_e32 v81, v0
	v_mov_b32_e32 v82, v0
	v_mov_b32_e32 v83, v0
	v_mov_b32_e32 v84, v0
	v_mov_b32_e32 v85, v0
	v_mov_b32_e32 v86, v0
	v_mov_b32_e32 v87, v0
	v_mov_b32_e32 v96, v0
	v_mov_b32_e32 v97, v0
	v_mov_b32_e32 v98, v0
	v_mov_b32_e32 v99, v0
	v_mov_b32_e32 v100, v0
	v_mov_b32_e32 v101, v0
	v_mov_b32_e32 v102, v0
	v_mov_b32_e32 v103, v0
	v_mov_b32_e32 v112, v0
	v_mov_b32_e32 v113, v0
	v_mov_b32_e32 v114, v0
	v_mov_b32_e32 v115, v0
	v_mov_b32_e32 v116, v0
	v_mov_b32_e32 v117, v0
	v_mov_b32_e32 v118, v0
	v_mov_b32_e32 v119, v0
	v_mov_b32_e32 v120, v0
	v_mov_b32_e32 v121, v0
	v_mov_b32_e32 v122, v0
	v_mov_b32_e32 v123, v0
	v_mov_b32_e32 v124, v0
	v_mov_b32_e32 v125, v0
	v_mov_b32_e32 v126, v0
	v_mov_b32_e32 v127, v0
.LBB0_747:
	ds_read_b128 v[150:153], v147
	ds_read_b128 v[154:157], v147 offset:1024
	ds_read_b128 v[158:161], v147 offset:2048
	ds_read_b128 v[162:165], v147 offset:3072
	ds_read_b128 v[166:169], v148
	ds_read_b128 v[170:173], v148 offset:1024
	ds_read_b128 v[174:177], v148 offset:2048
	ds_read_b128 v[178:181], v148 offset:3072
	s_add_u32 s52, s50, 0xfff00080
	s_addc_u32 s53, s51, -1
	s_cmp_eq_u32 s82, s100
	s_cselect_b32 s55, s41, s53
	s_cselect_b32 s54, s78, s52
	s_cselect_b32 s53, s43, s81
	s_cselect_b32 s52, s79, s80
	v_lshl_add_u64 v[186:187], s[50:51], 0, v[136:137]
	s_add_i32 m0, s45, 0xc000
	ds_read_b128 v[182:185], v149
	ds_read_b128 v[190:193], v149 offset:1024
	ds_read_b128 v[194:197], v149 offset:2048
	ds_read_b128 v[198:201], v149 offset:3072
	ds_read_b128 v[202:205], v149 offset:4096
	ds_read_b128 v[206:209], v149 offset:5120
	ds_read_b128 v[210:213], v149 offset:6144
	ds_read_b128 v[214:217], v149 offset:7168
	global_load_lds_dwordx4 v[186:187], off
	v_lshl_add_u64 v[186:187], s[50:51], 0, v[138:139]
	s_add_i32 m0, s45, 0xe000
	s_nop 0
	global_load_lds_dwordx4 v[186:187], off
	s_waitcnt vmcnt(8)
	s_waitcnt lgkmcnt(0)
	s_barrier
	s_setprio 1
	s_waitcnt lgkmcnt(0)
	v_mfma_f32_16x16x32_bf16 v[124:127], v[150:153], v[182:185], v[124:127]
	v_mfma_f32_16x16x32_bf16 v[120:123], v[158:161], v[182:185], v[120:123]
	v_mfma_f32_16x16x32_bf16 v[116:119], v[150:153], v[194:197], v[116:119]
	v_mfma_f32_16x16x32_bf16 v[112:115], v[158:161], v[194:197], v[112:115]
	v_mfma_f32_16x16x32_bf16 v[100:103], v[150:153], v[202:205], v[100:103]
	v_mfma_f32_16x16x32_bf16 v[96:99], v[158:161], v[202:205], v[96:99]
	v_mfma_f32_16x16x32_bf16 v[84:87], v[150:153], v[210:213], v[84:87]
	v_mfma_f32_16x16x32_bf16 v[80:83], v[158:161], v[210:213], v[80:83]
	v_mfma_f32_16x16x32_bf16 v[124:127], v[154:157], v[190:193], v[124:127]
	v_mfma_f32_16x16x32_bf16 v[120:123], v[162:165], v[190:193], v[120:123]
	v_mfma_f32_16x16x32_bf16 v[116:119], v[154:157], v[198:201], v[116:119]
	v_mfma_f32_16x16x32_bf16 v[112:115], v[162:165], v[198:201], v[112:115]
	v_mfma_f32_16x16x32_bf16 v[100:103], v[154:157], v[206:209], v[100:103]
	v_mfma_f32_16x16x32_bf16 v[96:99], v[162:165], v[206:209], v[96:99]
	v_mfma_f32_16x16x32_bf16 v[84:87], v[154:157], v[214:217], v[84:87]
	v_mfma_f32_16x16x32_bf16 v[80:83], v[162:165], v[214:217], v[80:83]
	s_setprio 0
	s_setprio 1
	v_mfma_f32_16x16x32_bf16 v[108:111], v[166:169], v[182:185], v[108:111]
	v_mfma_f32_16x16x32_bf16 v[104:107], v[174:177], v[182:185], v[104:107]
	v_mfma_f32_16x16x32_bf16 v[92:95], v[166:169], v[194:197], v[92:95]
	v_mfma_f32_16x16x32_bf16 v[88:91], v[174:177], v[194:197], v[88:91]
	v_mfma_f32_16x16x32_bf16 v[76:79], v[166:169], v[202:205], v[76:79]
	v_mfma_f32_16x16x32_bf16 v[72:75], v[174:177], v[202:205], v[72:75]
	v_mfma_f32_16x16x32_bf16 v[68:71], v[166:169], v[210:213], v[68:71]
	v_mfma_f32_16x16x32_bf16 v[64:67], v[174:177], v[210:213], v[64:67]
	v_mfma_f32_16x16x32_bf16 v[108:111], v[170:173], v[190:193], v[108:111]
	v_mfma_f32_16x16x32_bf16 v[104:107], v[178:181], v[190:193], v[104:107]
	v_mfma_f32_16x16x32_bf16 v[92:95], v[170:173], v[198:201], v[92:95]
	v_mfma_f32_16x16x32_bf16 v[88:91], v[178:181], v[198:201], v[88:91]
	v_mfma_f32_16x16x32_bf16 v[76:79], v[170:173], v[206:209], v[76:79]
	v_mfma_f32_16x16x32_bf16 v[72:75], v[178:181], v[206:209], v[72:75]
	v_mfma_f32_16x16x32_bf16 v[68:71], v[170:173], v[214:217], v[68:71]
	v_mfma_f32_16x16x32_bf16 v[64:67], v[178:181], v[214:217], v[64:67]
	s_setprio 0
	s_barrier
	s_add_i32 s62, s71, s58
	v_lshl_add_u64 v[186:187], s[52:53], 0, v[132:133]
	s_mov_b32 m0, s62
	ds_read_b128 v[182:185], v149 offset:16384
	ds_read_b128 v[190:193], v149 offset:17408
	ds_read_b128 v[194:197], v149 offset:18432
	ds_read_b128 v[198:201], v149 offset:19456
	ds_read_b128 v[202:205], v149 offset:20480
	ds_read_b128 v[206:209], v149 offset:21504
	ds_read_b128 v[210:213], v149 offset:22528
	ds_read_b128 v[214:217], v149 offset:23552
	global_load_lds_dwordx4 v[186:187], off
	s_add_i32 m0, s62, 0x2000
	s_add_u32 s84, s52, 0x100000
	v_lshl_add_u64 v[218:219], s[52:53], 0, v[128:129]
	s_addc_u32 s85, s53, 0
	s_add_i32 s62, s72, s58
	global_load_lds_dwordx4 v[218:219], off
	v_lshl_add_u64 v[220:221], s[84:85], 0, v[132:133]
	s_mov_b32 m0, s62
	v_lshl_add_u64 v[222:223], s[54:55], 0, v[130:131]
	global_load_lds_dwordx4 v[220:221], off
	v_lshl_add_u64 v[220:221], s[84:85], 0, v[128:129]
	s_add_i32 m0, s62, 0x2000
	s_nop 0
	global_load_lds_dwordx4 v[220:221], off
	v_lshl_add_u64 v[220:221], s[54:55], 0, v[134:135]
	s_mov_b32 m0, s45
	s_nop 0
	global_load_lds_dwordx4 v[220:221], off
	s_mov_b32 m0, s60
	s_nop 0
	global_load_lds_dwordx4 v[222:223], off
	s_waitcnt vmcnt(8)
	s_waitcnt lgkmcnt(0)
	s_barrier
	s_setprio 1
	s_waitcnt lgkmcnt(0)
	v_mfma_f32_16x16x32_bf16 v[60:63], v[150:153], v[182:185], v[60:63]
	v_mfma_f32_16x16x32_bf16 v[56:59], v[158:161], v[182:185], v[56:59]
	v_mfma_f32_16x16x32_bf16 v[52:55], v[150:153], v[194:197], v[52:55]
	v_mfma_f32_16x16x32_bf16 v[48:51], v[158:161], v[194:197], v[48:51]
	v_mfma_f32_16x16x32_bf16 v[36:39], v[150:153], v[202:205], v[36:39]
	v_mfma_f32_16x16x32_bf16 v[32:35], v[158:161], v[202:205], v[32:35]
	v_mfma_f32_16x16x32_bf16 v[20:23], v[150:153], v[210:213], v[20:23]
	v_mfma_f32_16x16x32_bf16 v[16:19], v[158:161], v[210:213], v[16:19]
	v_mfma_f32_16x16x32_bf16 v[60:63], v[154:157], v[190:193], v[60:63]
	v_mfma_f32_16x16x32_bf16 v[56:59], v[162:165], v[190:193], v[56:59]
	v_mfma_f32_16x16x32_bf16 v[52:55], v[154:157], v[198:201], v[52:55]
	v_mfma_f32_16x16x32_bf16 v[48:51], v[162:165], v[198:201], v[48:51]
	v_mfma_f32_16x16x32_bf16 v[36:39], v[154:157], v[206:209], v[36:39]
	v_mfma_f32_16x16x32_bf16 v[32:35], v[162:165], v[206:209], v[32:35]
	v_mfma_f32_16x16x32_bf16 v[20:23], v[154:157], v[214:217], v[20:23]
	v_mfma_f32_16x16x32_bf16 v[16:19], v[162:165], v[214:217], v[16:19]
	s_setprio 0
	s_setprio 1
	v_mfma_f32_16x16x32_bf16 v[44:47], v[166:169], v[182:185], v[44:47]
	v_mfma_f32_16x16x32_bf16 v[40:43], v[174:177], v[182:185], v[40:43]
	v_mfma_f32_16x16x32_bf16 v[28:31], v[166:169], v[194:197], v[28:31]
	v_mfma_f32_16x16x32_bf16 v[24:27], v[174:177], v[194:197], v[24:27]
	v_mfma_f32_16x16x32_bf16 v[12:15], v[166:169], v[202:205], v[12:15]
	v_mfma_f32_16x16x32_bf16 v[8:11], v[174:177], v[202:205], v[8:11]
	v_mfma_f32_16x16x32_bf16 v[4:7], v[166:169], v[210:213], v[4:7]
	v_mfma_f32_16x16x32_bf16 v[0:3], v[174:177], v[210:213], v[0:3]
	v_mfma_f32_16x16x32_bf16 v[44:47], v[170:173], v[190:193], v[44:47]
	v_mfma_f32_16x16x32_bf16 v[40:43], v[178:181], v[190:193], v[40:43]
	v_mfma_f32_16x16x32_bf16 v[28:31], v[170:173], v[198:201], v[28:31]
	v_mfma_f32_16x16x32_bf16 v[24:27], v[178:181], v[198:201], v[24:27]
	v_mfma_f32_16x16x32_bf16 v[12:15], v[170:173], v[206:209], v[12:15]
	v_mfma_f32_16x16x32_bf16 v[8:11], v[178:181], v[206:209], v[8:11]
	v_mfma_f32_16x16x32_bf16 v[4:7], v[170:173], v[214:217], v[4:7]
	v_mfma_f32_16x16x32_bf16 v[0:3], v[178:181], v[214:217], v[0:3]
	s_setprio 0
	s_barrier
	s_add_i32 s62, 0, 0x18000
	s_add_i32 s64, 0, 0x1c000
	v_add_u32_e32 v162, s62, v145
	v_add_u32_e32 v178, s64, v145
	ds_read_b128 v[150:153], v162
	ds_read_b128 v[154:157], v162 offset:1024
	ds_read_b128 v[158:161], v162 offset:2048
	ds_read_b128 v[162:165], v162 offset:3072
	ds_read_b128 v[166:169], v178
	ds_read_b128 v[170:173], v178 offset:1024
	ds_read_b128 v[174:177], v178 offset:2048
	ds_read_b128 v[178:181], v178 offset:3072
	s_add_u32 s54, s54, 0x100000
	s_addc_u32 s55, s55, 0
	s_mov_b32 m0, s61
	v_lshl_add_u64 v[224:225], s[54:55], 0, v[134:135]
	ds_read_b128 v[182:185], v149 offset:32768
	ds_read_b128 v[190:193], v149 offset:33792
	ds_read_b128 v[194:197], v149 offset:34816
	ds_read_b128 v[198:201], v149 offset:35840
	ds_read_b128 v[202:205], v149 offset:36864
	ds_read_b128 v[206:209], v149 offset:37888
	ds_read_b128 v[210:213], v149 offset:38912
	ds_read_b128 v[214:217], v149 offset:39936
	global_load_lds_dwordx4 v[224:225], off
	v_lshl_add_u64 v[224:225], s[54:55], 0, v[130:131]
	s_mov_b32 m0, s63
	s_nop 0
	global_load_lds_dwordx4 v[224:225], off
	s_waitcnt vmcnt(8)
	s_waitcnt lgkmcnt(0)
	s_barrier
	s_setprio 1
	s_waitcnt lgkmcnt(0)
	v_mfma_f32_16x16x32_bf16 v[124:127], v[150:153], v[182:185], v[124:127]
	v_mfma_f32_16x16x32_bf16 v[120:123], v[158:161], v[182:185], v[120:123]
	v_mfma_f32_16x16x32_bf16 v[116:119], v[150:153], v[194:197], v[116:119]
	v_mfma_f32_16x16x32_bf16 v[112:115], v[158:161], v[194:197], v[112:115]
	v_mfma_f32_16x16x32_bf16 v[100:103], v[150:153], v[202:205], v[100:103]
	v_mfma_f32_16x16x32_bf16 v[96:99], v[158:161], v[202:205], v[96:99]
	v_mfma_f32_16x16x32_bf16 v[84:87], v[150:153], v[210:213], v[84:87]
	v_mfma_f32_16x16x32_bf16 v[80:83], v[158:161], v[210:213], v[80:83]
	v_mfma_f32_16x16x32_bf16 v[124:127], v[154:157], v[190:193], v[124:127]
	v_mfma_f32_16x16x32_bf16 v[120:123], v[162:165], v[190:193], v[120:123]
	v_mfma_f32_16x16x32_bf16 v[116:119], v[154:157], v[198:201], v[116:119]
	v_mfma_f32_16x16x32_bf16 v[112:115], v[162:165], v[198:201], v[112:115]
	v_mfma_f32_16x16x32_bf16 v[100:103], v[154:157], v[206:209], v[100:103]
	v_mfma_f32_16x16x32_bf16 v[96:99], v[162:165], v[206:209], v[96:99]
	v_mfma_f32_16x16x32_bf16 v[84:87], v[154:157], v[214:217], v[84:87]
	v_mfma_f32_16x16x32_bf16 v[80:83], v[162:165], v[214:217], v[80:83]
	s_setprio 0
	s_setprio 1
	v_mfma_f32_16x16x32_bf16 v[108:111], v[166:169], v[182:185], v[108:111]
	v_mfma_f32_16x16x32_bf16 v[104:107], v[174:177], v[182:185], v[104:107]
	v_mfma_f32_16x16x32_bf16 v[92:95], v[166:169], v[194:197], v[92:95]
	v_mfma_f32_16x16x32_bf16 v[88:91], v[174:177], v[194:197], v[88:91]
	v_mfma_f32_16x16x32_bf16 v[76:79], v[166:169], v[202:205], v[76:79]
	v_mfma_f32_16x16x32_bf16 v[72:75], v[174:177], v[202:205], v[72:75]
	v_mfma_f32_16x16x32_bf16 v[68:71], v[166:169], v[210:213], v[68:71]
	v_mfma_f32_16x16x32_bf16 v[64:67], v[174:177], v[210:213], v[64:67]
	v_mfma_f32_16x16x32_bf16 v[108:111], v[170:173], v[190:193], v[108:111]
	v_mfma_f32_16x16x32_bf16 v[104:107], v[178:181], v[190:193], v[104:107]
	v_mfma_f32_16x16x32_bf16 v[92:95], v[170:173], v[198:201], v[92:95]
	v_mfma_f32_16x16x32_bf16 v[88:91], v[178:181], v[198:201], v[88:91]
	v_mfma_f32_16x16x32_bf16 v[76:79], v[170:173], v[206:209], v[76:79]
	v_mfma_f32_16x16x32_bf16 v[72:75], v[178:181], v[206:209], v[72:75]
	v_mfma_f32_16x16x32_bf16 v[68:71], v[170:173], v[214:217], v[68:71]
	v_mfma_f32_16x16x32_bf16 v[64:67], v[178:181], v[214:217], v[64:67]
	s_setprio 0
	s_barrier
	s_add_i32 s54, s62, s58
	v_lshl_add_u64 v[186:187], v[186:187], 0, s[12:13]
	s_mov_b32 m0, s54
	ds_read_b128 v[182:185], v149 offset:49152
	ds_read_b128 v[190:193], v149 offset:50176
	ds_read_b128 v[194:197], v149 offset:51200
	ds_read_b128 v[198:201], v149 offset:52224
	ds_read_b128 v[202:205], v149 offset:53248
	ds_read_b128 v[206:209], v149 offset:54272
	ds_read_b128 v[210:213], v149 offset:55296
	ds_read_b128 v[214:217], v149 offset:56320
	global_load_lds_dwordx4 v[186:187], off
	s_add_i32 m0, s54, 0x2000
	s_add_u32 s52, s52, 0x100080
	v_lshl_add_u64 v[186:187], v[218:219], 0, s[12:13]
	s_addc_u32 s53, s53, 0
	s_add_i32 s54, s64, s58
	global_load_lds_dwordx4 v[186:187], off
	v_lshl_add_u64 v[186:187], s[52:53], 0, v[132:133]
	s_mov_b32 m0, s54
	s_nop 0
	global_load_lds_dwordx4 v[186:187], off
	v_lshl_add_u64 v[186:187], s[52:53], 0, v[128:129]
	s_add_i32 m0, s54, 0x2000
	s_nop 0
	global_load_lds_dwordx4 v[186:187], off
	v_lshl_add_u64 v[186:187], v[220:221], 0, s[12:13]
	s_mov_b32 m0, s66
	s_nop 0
	global_load_lds_dwordx4 v[186:187], off
	v_lshl_add_u64 v[186:187], v[222:223], 0, s[12:13]
	s_mov_b32 m0, s67
	s_nop 0
	global_load_lds_dwordx4 v[186:187], off
	s_waitcnt vmcnt(8)
	s_waitcnt lgkmcnt(0)
	s_barrier
	s_setprio 1
	s_waitcnt lgkmcnt(0)
	v_mfma_f32_16x16x32_bf16 v[60:63], v[150:153], v[182:185], v[60:63]
	v_mfma_f32_16x16x32_bf16 v[56:59], v[158:161], v[182:185], v[56:59]
	v_mfma_f32_16x16x32_bf16 v[52:55], v[150:153], v[194:197], v[52:55]
	v_mfma_f32_16x16x32_bf16 v[48:51], v[158:161], v[194:197], v[48:51]
	v_mfma_f32_16x16x32_bf16 v[36:39], v[150:153], v[202:205], v[36:39]
	v_mfma_f32_16x16x32_bf16 v[32:35], v[158:161], v[202:205], v[32:35]
	v_mfma_f32_16x16x32_bf16 v[20:23], v[150:153], v[210:213], v[20:23]
	v_mfma_f32_16x16x32_bf16 v[16:19], v[158:161], v[210:213], v[16:19]
	v_mfma_f32_16x16x32_bf16 v[60:63], v[154:157], v[190:193], v[60:63]
	v_mfma_f32_16x16x32_bf16 v[56:59], v[162:165], v[190:193], v[56:59]
	v_mfma_f32_16x16x32_bf16 v[52:55], v[154:157], v[198:201], v[52:55]
	v_mfma_f32_16x16x32_bf16 v[48:51], v[162:165], v[198:201], v[48:51]
	v_mfma_f32_16x16x32_bf16 v[36:39], v[154:157], v[206:209], v[36:39]
	v_mfma_f32_16x16x32_bf16 v[32:35], v[162:165], v[206:209], v[32:35]
	v_mfma_f32_16x16x32_bf16 v[20:23], v[154:157], v[214:217], v[20:23]
	v_mfma_f32_16x16x32_bf16 v[16:19], v[162:165], v[214:217], v[16:19]
	s_setprio 0
	s_setprio 1
	v_mfma_f32_16x16x32_bf16 v[44:47], v[166:169], v[182:185], v[44:47]
	v_mfma_f32_16x16x32_bf16 v[40:43], v[174:177], v[182:185], v[40:43]
	v_mfma_f32_16x16x32_bf16 v[28:31], v[166:169], v[194:197], v[28:31]
	v_mfma_f32_16x16x32_bf16 v[24:27], v[174:177], v[194:197], v[24:27]
	v_mfma_f32_16x16x32_bf16 v[12:15], v[166:169], v[202:205], v[12:15]
	v_mfma_f32_16x16x32_bf16 v[8:11], v[174:177], v[202:205], v[8:11]
	v_mfma_f32_16x16x32_bf16 v[4:7], v[166:169], v[210:213], v[4:7]
	v_mfma_f32_16x16x32_bf16 v[0:3], v[174:177], v[210:213], v[0:3]
	v_mfma_f32_16x16x32_bf16 v[44:47], v[170:173], v[190:193], v[44:47]
	v_mfma_f32_16x16x32_bf16 v[40:43], v[178:181], v[190:193], v[40:43]
	v_mfma_f32_16x16x32_bf16 v[28:31], v[170:173], v[198:201], v[28:31]
	v_mfma_f32_16x16x32_bf16 v[24:27], v[178:181], v[198:201], v[24:27]
	v_mfma_f32_16x16x32_bf16 v[12:15], v[170:173], v[206:209], v[12:15]
	v_mfma_f32_16x16x32_bf16 v[8:11], v[178:181], v[206:209], v[8:11]
	v_mfma_f32_16x16x32_bf16 v[4:7], v[170:173], v[214:217], v[4:7]
	v_mfma_f32_16x16x32_bf16 v[0:3], v[178:181], v[214:217], v[0:3]
	s_setprio 0
	s_barrier
	s_add_i32 s82, s82, 2
	s_add_u32 s50, s50, 0x100
	s_addc_u32 s51, s51, 0
	s_add_u32 s80, s80, 0x100
	s_addc_u32 s81, s81, 0
	s_cmp_gt_u32 s82, s100
	s_cbranch_scc0 .LBB0_747
	s_cmp_lt_u32 s98, 3
	s_cbranch_scc0 .Lsk8_notc
	s_cmp_eq_u32 s68, 2
	s_cbranch_scc1 .LBB0_742
.Lsk8_notc:
	s_and_b64 vcc, exec, s[16:17]
	s_cbranch_vccz .LBB0_750
	s_barrier
.LBB0_750:
	s_cmp_eq_u32 s98, 3
	s_cbranch_scc1 .Lsk8_d3
	s_cmp_eq_u32 s68, 1
	s_cbranch_scc1 .Lsk8_pstore
	s_branch .Lsk8_epi
.Lsk8_d3:
	s_cmp_eq_u32 s68, 2
	s_cbranch_scc1 .Lsk8_rload

.Lsk8_pstore:
	s_mul_i32 s54, s99, 3
	s_add_i32 s54, s54, s98
	s_lshl_b32 s55, s54, 2
	s_lshl_b32 s54, s54, 18
	s_add_u32 s84, s6, 0xc800000
	s_addc_u32 s85, s7, 0
	s_add_u32 s84, s84, s54
	s_addc_u32 s85, s85, 0
	s_movk_i32 s62, 0x2000
	v_lshlrev_b32_e32 v150, 4, v188
	global_store_dwordx4 v150, v[0:3], s[84:85] sc1
	s_add_u32 s84, s84, s62
	s_addc_u32 s85, s85, 0
	global_store_dwordx4 v150, v[4:7], s[84:85] sc1
	s_add_u32 s84, s84, s62
	s_addc_u32 s85, s85, 0
	global_store_dwordx4 v150, v[8:11], s[84:85] sc1
	s_add_u32 s84, s84, s62
	s_addc_u32 s85, s85, 0
	global_store_dwordx4 v150, v[12:15], s[84:85] sc1
	s_add_u32 s84, s84, s62
	s_addc_u32 s85, s85, 0
	global_store_dwordx4 v150, v[16:19], s[84:85] sc1
	s_add_u32 s84, s84, s62
	s_addc_u32 s85, s85, 0
	global_store_dwordx4 v150, v[20:23], s[84:85] sc1
	s_add_u32 s84, s84, s62
	s_addc_u32 s85, s85, 0
	global_store_dwordx4 v150, v[24:27], s[84:85] sc1
	s_add_u32 s84, s84, s62
	s_addc_u32 s85, s85, 0
	global_store_dwordx4 v150, v[28:31], s[84:85] sc1
	s_add_u32 s84, s84, s62
	s_addc_u32 s85, s85, 0
	global_store_dwordx4 v150, v[32:35], s[84:85] sc1
	s_add_u32 s84, s84, s62
	s_addc_u32 s85, s85, 0
	global_store_dwordx4 v150, v[36:39], s[84:85] sc1
	s_add_u32 s84, s84, s62
	s_addc_u32 s85, s85, 0
	global_store_dwordx4 v150, v[40:43], s[84:85] sc1
	s_add_u32 s84, s84, s62
	s_addc_u32 s85, s85, 0
	global_store_dwordx4 v150, v[44:47], s[84:85] sc1
	s_add_u32 s84, s84, s62
	s_addc_u32 s85, s85, 0
	global_store_dwordx4 v150, v[48:51], s[84:85] sc1
	s_add_u32 s84, s84, s62
	s_addc_u32 s85, s85, 0
	global_store_dwordx4 v150, v[52:55], s[84:85] sc1
	s_add_u32 s84, s84, s62
	s_addc_u32 s85, s85, 0
	global_store_dwordx4 v150, v[56:59], s[84:85] sc1
	s_add_u32 s84, s84, s62
	s_addc_u32 s85, s85, 0
	global_store_dwordx4 v150, v[60:63], s[84:85] sc1
	s_add_u32 s84, s84, s62
	s_addc_u32 s85, s85, 0
	global_store_dwordx4 v150, v[64:67], s[84:85] sc1
	s_add_u32 s84, s84, s62
	s_addc_u32 s85, s85, 0
	global_store_dwordx4 v150, v[68:71], s[84:85] sc1
	s_add_u32 s84, s84, s62
	s_addc_u32 s85, s85, 0
	global_store_dwordx4 v150, v[72:75], s[84:85] sc1
	s_add_u32 s84, s84, s62
	s_addc_u32 s85, s85, 0
	global_store_dwordx4 v150, v[76:79], s[84:85] sc1
	s_add_u32 s84, s84, s62
	s_addc_u32 s85, s85, 0
	global_store_dwordx4 v150, v[80:83], s[84:85] sc1
	s_add_u32 s84, s84, s62
	s_addc_u32 s85, s85, 0
	global_store_dwordx4 v150, v[84:87], s[84:85] sc1
	s_add_u32 s84, s84, s62
	s_addc_u32 s85, s85, 0
	global_store_dwordx4 v150, v[88:91], s[84:85] sc1
	s_add_u32 s84, s84, s62
	s_addc_u32 s85, s85, 0
	global_store_dwordx4 v150, v[92:95], s[84:85] sc1
	s_add_u32 s84, s84, s62
	s_addc_u32 s85, s85, 0
	global_store_dwordx4 v150, v[96:99], s[84:85] sc1
	s_add_u32 s84, s84, s62
	s_addc_u32 s85, s85, 0
	global_store_dwordx4 v150, v[100:103], s[84:85] sc1
	s_add_u32 s84, s84, s62
	s_addc_u32 s85, s85, 0
	global_store_dwordx4 v150, v[104:107], s[84:85] sc1
	s_add_u32 s84, s84, s62
	s_addc_u32 s85, s85, 0
	global_store_dwordx4 v150, v[108:111], s[84:85] sc1
	s_add_u32 s84, s84, s62
	s_addc_u32 s85, s85, 0
	global_store_dwordx4 v150, v[112:115], s[84:85] sc1
	s_add_u32 s84, s84, s62
	s_addc_u32 s85, s85, 0
	global_store_dwordx4 v150, v[116:119], s[84:85] sc1
	s_add_u32 s84, s84, s62
	s_addc_u32 s85, s85, 0
	global_store_dwordx4 v150, v[120:123], s[84:85] sc1
	s_add_u32 s84, s84, s62
	s_addc_u32 s85, s85, 0
	global_store_dwordx4 v150, v[124:127], s[84:85] sc1
	s_waitcnt vmcnt(0)
	s_barrier
	s_and_saveexec_b64 s[80:81], s[14:15]
	s_cbranch_execz .Lsk8_pdone
	v_mov_b32_e32 v151, 1
	v_mov_b32_e32 v152, s55
	v_add_u32_e32 v152, 0x3600, v152
	global_store_dword v152, v151, s[24:25] sc1
.Lsk8_pdone:
	s_or_b64 exec, exec, s[80:81]
	s_andn2_b64 vcc, exec, s[4:5]
	s_mov_b64 s[4:5], -1
	s_cbranch_vccnz .LBB0_743
	s_andn2_b64 vcc, exec, s[8:9]
	s_cbranch_vccnz .LBB0_742
	s_barrier
	s_branch .LBB0_742
.Lsk8_rload:
	s_mul_i32 s54, s99, 3
	s_lshl_b32 s55, s54, 2
	s_lshl_b32 s54, s54, 18
	s_add_u32 s84, s6, 0xc800000
	s_addc_u32 s85, s7, 0
	s_add_u32 s84, s84, s54
	s_addc_u32 s85, s85, 0
	s_movk_i32 s62, 0x2000
	v_lshlrev_b32_e32 v150, 4, v188
	s_and_saveexec_b64 s[80:81], s[14:15]
	s_cbranch_execz .Lsk8_polled
	v_mov_b32_e32 v152, s55
	v_add_u32_e32 v152, 0x3600, v152
	s_mov_b32 s64, 0
.Lsk8_poll:
	global_load_dword v151, v152, s[24:25] sc1
	global_load_dword v153, v152, s[24:25] offset:4 sc1
	global_load_dword v154, v152, s[24:25] offset:8 sc1
	s_waitcnt vmcnt(0)
	v_and_b32_e32 v151, v151, v153
	v_and_b32_e32 v151, v151, v154
	s_nop 0
	v_readfirstlane_b32 s54, v151
	s_cmp_lg_u32 s54, 0
	s_cbranch_scc1 .Lsk8_polled
	s_sleep 1
	s_add_i32 s64, s64, 1
	s_cmp_lt_u32 s64, 0x4000
	s_cbranch_scc1 .Lsk8_poll
.Lsk8_polled:
	s_or_b64 exec, exec, s[80:81]
	s_barrier
	global_load_dwordx4 v[152:155], v150, s[84:85] sc1
	s_add_u32 s84, s84, s62
	s_addc_u32 s85, s85, 0
	global_load_dwordx4 v[156:159], v150, s[84:85] sc1
	s_add_u32 s84, s84, s62
	s_addc_u32 s85, s85, 0
	global_load_dwordx4 v[160:163], v150, s[84:85] sc1
	s_add_u32 s84, s84, s62
	s_addc_u32 s85, s85, 0
	global_load_dwordx4 v[164:167], v150, s[84:85] sc1
	s_add_u32 s84, s84, s62
	s_addc_u32 s85, s85, 0
	global_load_dwordx4 v[168:171], v150, s[84:85] sc1
	s_add_u32 s84, s84, s62
	s_addc_u32 s85, s85, 0
	global_load_dwordx4 v[172:175], v150, s[84:85] sc1
	s_add_u32 s84, s84, s62
	s_addc_u32 s85, s85, 0
	global_load_dwordx4 v[176:179], v150, s[84:85] sc1
	s_add_u32 s84, s84, s62
	s_addc_u32 s85, s85, 0
	global_load_dwordx4 v[180:183], v150, s[84:85] sc1
	s_add_u32 s84, s84, s62
	s_addc_u32 s85, s85, 0
	global_load_dwordx4 v[184:187], v150, s[84:85] sc1
	s_add_u32 s84, s84, s62
	s_addc_u32 s85, s85, 0
	global_load_dwordx4 v[192:195], v150, s[84:85] sc1
	s_add_u32 s84, s84, s62
	s_addc_u32 s85, s85, 0
	global_load_dwordx4 v[196:199], v150, s[84:85] sc1
	s_add_u32 s84, s84, s62
	s_addc_u32 s85, s85, 0
	global_load_dwordx4 v[200:203], v150, s[84:85] sc1
	s_add_u32 s84, s84, s62
	s_addc_u32 s85, s85, 0
	global_load_dwordx4 v[204:207], v150, s[84:85] sc1
	s_add_u32 s84, s84, s62
	s_addc_u32 s85, s85, 0
	global_load_dwordx4 v[208:211], v150, s[84:85] sc1
	s_add_u32 s84, s84, s62
	s_addc_u32 s85, s85, 0
	global_load_dwordx4 v[212:215], v150, s[84:85] sc1
	s_add_u32 s84, s84, s62
	s_addc_u32 s85, s85, 0
	global_load_dwordx4 v[216:219], v150, s[84:85] sc1
	s_add_u32 s84, s84, s62
	s_addc_u32 s85, s85, 0
	s_waitcnt vmcnt(15)
	v_pk_add_f32 v[0:1], v[0:1], v[152:153]
	v_pk_add_f32 v[2:3], v[2:3], v[154:155]
	s_waitcnt vmcnt(14)
	v_pk_add_f32 v[4:5], v[4:5], v[156:157]
	v_pk_add_f32 v[6:7], v[6:7], v[158:159]
	s_waitcnt vmcnt(13)
	v_pk_add_f32 v[8:9], v[8:9], v[160:161]
	v_pk_add_f32 v[10:11], v[10:11], v[162:163]
	s_waitcnt vmcnt(12)
	v_pk_add_f32 v[12:13], v[12:13], v[164:165]
	v_pk_add_f32 v[14:15], v[14:15], v[166:167]
	s_waitcnt vmcnt(11)
	v_pk_add_f32 v[16:17], v[16:17], v[168:169]
	v_pk_add_f32 v[18:19], v[18:19], v[170:171]
	s_waitcnt vmcnt(10)
	v_pk_add_f32 v[20:21], v[20:21], v[172:173]
	v_pk_add_f32 v[22:23], v[22:23], v[174:175]
	s_waitcnt vmcnt(9)
	v_pk_add_f32 v[24:25], v[24:25], v[176:177]
	v_pk_add_f32 v[26:27], v[26:27], v[178:179]
	s_waitcnt vmcnt(8)
	v_pk_add_f32 v[28:29], v[28:29], v[180:181]
	v_pk_add_f32 v[30:31], v[30:31], v[182:183]
	s_waitcnt vmcnt(7)
	v_pk_add_f32 v[32:33], v[32:33], v[184:185]
	v_pk_add_f32 v[34:35], v[34:35], v[186:187]
	s_waitcnt vmcnt(6)
	v_pk_add_f32 v[36:37], v[36:37], v[192:193]
	v_pk_add_f32 v[38:39], v[38:39], v[194:195]
	s_waitcnt vmcnt(5)
	v_pk_add_f32 v[40:41], v[40:41], v[196:197]
	v_pk_add_f32 v[42:43], v[42:43], v[198:199]
	s_waitcnt vmcnt(4)
	v_pk_add_f32 v[44:45], v[44:45], v[200:201]
	v_pk_add_f32 v[46:47], v[46:47], v[202:203]
	s_waitcnt vmcnt(3)
	v_pk_add_f32 v[48:49], v[48:49], v[204:205]
	v_pk_add_f32 v[50:51], v[50:51], v[206:207]
	s_waitcnt vmcnt(2)
	v_pk_add_f32 v[52:53], v[52:53], v[208:209]
	v_pk_add_f32 v[54:55], v[54:55], v[210:211]
	s_waitcnt vmcnt(1)
	v_pk_add_f32 v[56:57], v[56:57], v[212:213]
	v_pk_add_f32 v[58:59], v[58:59], v[214:215]
	s_waitcnt vmcnt(0)
	v_pk_add_f32 v[60:61], v[60:61], v[216:217]
	v_pk_add_f32 v[62:63], v[62:63], v[218:219]
	global_load_dwordx4 v[152:155], v150, s[84:85] sc1
	s_add_u32 s84, s84, s62
	s_addc_u32 s85, s85, 0
	global_load_dwordx4 v[156:159], v150, s[84:85] sc1
	s_add_u32 s84, s84, s62
	s_addc_u32 s85, s85, 0
	global_load_dwordx4 v[160:163], v150, s[84:85] sc1
	s_add_u32 s84, s84, s62
	s_addc_u32 s85, s85, 0
	global_load_dwordx4 v[164:167], v150, s[84:85] sc1
	s_add_u32 s84, s84, s62
	s_addc_u32 s85, s85, 0
	global_load_dwordx4 v[168:171], v150, s[84:85] sc1
	s_add_u32 s84, s84, s62
	s_addc_u32 s85, s85, 0
	global_load_dwordx4 v[172:175], v150, s[84:85] sc1
	s_add_u32 s84, s84, s62
	s_addc_u32 s85, s85, 0
	global_load_dwordx4 v[176:179], v150, s[84:85] sc1
	s_add_u32 s84, s84, s62
	s_addc_u32 s85, s85, 0
	global_load_dwordx4 v[180:183], v150, s[84:85] sc1
	s_add_u32 s84, s84, s62
	s_addc_u32 s85, s85, 0
	global_load_dwordx4 v[184:187], v150, s[84:85] sc1
	s_add_u32 s84, s84, s62
	s_addc_u32 s85, s85, 0
	global_load_dwordx4 v[192:195], v150, s[84:85] sc1
	s_add_u32 s84, s84, s62
	s_addc_u32 s85, s85, 0
	global_load_dwordx4 v[196:199], v150, s[84:85] sc1
	s_add_u32 s84, s84, s62
	s_addc_u32 s85, s85, 0
	global_load_dwordx4 v[200:203], v150, s[84:85] sc1
	s_add_u32 s84, s84, s62
	s_addc_u32 s85, s85, 0
	global_load_dwordx4 v[204:207], v150, s[84:85] sc1
	s_add_u32 s84, s84, s62
	s_addc_u32 s85, s85, 0
	global_load_dwordx4 v[208:211], v150, s[84:85] sc1
	s_add_u32 s84, s84, s62
	s_addc_u32 s85, s85, 0
	global_load_dwordx4 v[212:215], v150, s[84:85] sc1
	s_add_u32 s84, s84, s62
	s_addc_u32 s85, s85, 0
	global_load_dwordx4 v[216:219], v150, s[84:85] sc1
	s_add_u32 s84, s84, s62
	s_addc_u32 s85, s85, 0
	s_waitcnt vmcnt(15)
	v_pk_add_f32 v[64:65], v[64:65], v[152:153]
	v_pk_add_f32 v[66:67], v[66:67], v[154:155]
	s_waitcnt vmcnt(14)
	v_pk_add_f32 v[68:69], v[68:69], v[156:157]
	v_pk_add_f32 v[70:71], v[70:71], v[158:159]
	s_waitcnt vmcnt(13)
	v_pk_add_f32 v[72:73], v[72:73], v[160:161]
	v_pk_add_f32 v[74:75], v[74:75], v[162:163]
	s_waitcnt vmcnt(12)
	v_pk_add_f32 v[76:77], v[76:77], v[164:165]
	v_pk_add_f32 v[78:79], v[78:79], v[166:167]
	s_waitcnt vmcnt(11)
	v_pk_add_f32 v[80:81], v[80:81], v[168:169]
	v_pk_add_f32 v[82:83], v[82:83], v[170:171]
	s_waitcnt vmcnt(10)
	v_pk_add_f32 v[84:85], v[84:85], v[172:173]
	v_pk_add_f32 v[86:87], v[86:87], v[174:175]
	s_waitcnt vmcnt(9)
	v_pk_add_f32 v[88:89], v[88:89], v[176:177]
	v_pk_add_f32 v[90:91], v[90:91], v[178:179]
	s_waitcnt vmcnt(8)
	v_pk_add_f32 v[92:93], v[92:93], v[180:181]
	v_pk_add_f32 v[94:95], v[94:95], v[182:183]
	s_waitcnt vmcnt(7)
	v_pk_add_f32 v[96:97], v[96:97], v[184:185]
	v_pk_add_f32 v[98:99], v[98:99], v[186:187]
	s_waitcnt vmcnt(6)
	v_pk_add_f32 v[100:101], v[100:101], v[192:193]
	v_pk_add_f32 v[102:103], v[102:103], v[194:195]
	s_waitcnt vmcnt(5)
	v_pk_add_f32 v[104:105], v[104:105], v[196:197]
	v_pk_add_f32 v[106:107], v[106:107], v[198:199]
	s_waitcnt vmcnt(4)
	v_pk_add_f32 v[108:109], v[108:109], v[200:201]
	v_pk_add_f32 v[110:111], v[110:111], v[202:203]
	s_waitcnt vmcnt(3)
	v_pk_add_f32 v[112:113], v[112:113], v[204:205]
	v_pk_add_f32 v[114:115], v[114:115], v[206:207]
	s_waitcnt vmcnt(2)
	v_pk_add_f32 v[116:117], v[116:117], v[208:209]
	v_pk_add_f32 v[118:119], v[118:119], v[210:211]
	s_waitcnt vmcnt(1)
	v_pk_add_f32 v[120:121], v[120:121], v[212:213]
	v_pk_add_f32 v[122:123], v[122:123], v[214:215]
	s_waitcnt vmcnt(0)
	v_pk_add_f32 v[124:125], v[124:125], v[216:217]
	v_pk_add_f32 v[126:127], v[126:127], v[218:219]
	global_load_dwordx4 v[152:155], v150, s[84:85] sc1
	s_add_u32 s84, s84, s62
	s_addc_u32 s85, s85, 0
	global_load_dwordx4 v[156:159], v150, s[84:85] sc1
	s_add_u32 s84, s84, s62
	s_addc_u32 s85, s85, 0
	global_load_dwordx4 v[160:163], v150, s[84:85] sc1
	s_add_u32 s84, s84, s62
	s_addc_u32 s85, s85, 0
	global_load_dwordx4 v[164:167], v150, s[84:85] sc1
	s_add_u32 s84, s84, s62
	s_addc_u32 s85, s85, 0
	global_load_dwordx4 v[168:171], v150, s[84:85] sc1
	s_add_u32 s84, s84, s62
	s_addc_u32 s85, s85, 0
	global_load_dwordx4 v[172:175], v150, s[84:85] sc1
	s_add_u32 s84, s84, s62
	s_addc_u32 s85, s85, 0
	global_load_dwordx4 v[176:179], v150, s[84:85] sc1
	s_add_u32 s84, s84, s62
	s_addc_u32 s85, s85, 0
	global_load_dwordx4 v[180:183], v150, s[84:85] sc1
	s_add_u32 s84, s84, s62
	s_addc_u32 s85, s85, 0
	global_load_dwordx4 v[184:187], v150, s[84:85] sc1
	s_add_u32 s84, s84, s62
	s_addc_u32 s85, s85, 0
	global_load_dwordx4 v[192:195], v150, s[84:85] sc1
	s_add_u32 s84, s84, s62
	s_addc_u32 s85, s85, 0
	global_load_dwordx4 v[196:199], v150, s[84:85] sc1
	s_add_u32 s84, s84, s62
	s_addc_u32 s85, s85, 0
	global_load_dwordx4 v[200:203], v150, s[84:85] sc1
	s_add_u32 s84, s84, s62
	s_addc_u32 s85, s85, 0
	global_load_dwordx4 v[204:207], v150, s[84:85] sc1
	s_add_u32 s84, s84, s62
	s_addc_u32 s85, s85, 0
	global_load_dwordx4 v[208:211], v150, s[84:85] sc1
	s_add_u32 s84, s84, s62
	s_addc_u32 s85, s85, 0
	global_load_dwordx4 v[212:215], v150, s[84:85] sc1
	s_add_u32 s84, s84, s62
	s_addc_u32 s85, s85, 0
	global_load_dwordx4 v[216:219], v150, s[84:85] sc1
	s_add_u32 s84, s84, s62
	s_addc_u32 s85, s85, 0
	s_waitcnt vmcnt(15)
	v_pk_add_f32 v[0:1], v[0:1], v[152:153]
	v_pk_add_f32 v[2:3], v[2:3], v[154:155]
	s_waitcnt vmcnt(14)
	v_pk_add_f32 v[4:5], v[4:5], v[156:157]
	v_pk_add_f32 v[6:7], v[6:7], v[158:159]
	s_waitcnt vmcnt(13)
	v_pk_add_f32 v[8:9], v[8:9], v[160:161]
	v_pk_add_f32 v[10:11], v[10:11], v[162:163]
	s_waitcnt vmcnt(12)
	v_pk_add_f32 v[12:13], v[12:13], v[164:165]
	v_pk_add_f32 v[14:15], v[14:15], v[166:167]
	s_waitcnt vmcnt(11)
	v_pk_add_f32 v[16:17], v[16:17], v[168:169]
	v_pk_add_f32 v[18:19], v[18:19], v[170:171]
	s_waitcnt vmcnt(10)
	v_pk_add_f32 v[20:21], v[20:21], v[172:173]
	v_pk_add_f32 v[22:23], v[22:23], v[174:175]
	s_waitcnt vmcnt(9)
	v_pk_add_f32 v[24:25], v[24:25], v[176:177]
	v_pk_add_f32 v[26:27], v[26:27], v[178:179]
	s_waitcnt vmcnt(8)
	v_pk_add_f32 v[28:29], v[28:29], v[180:181]
	v_pk_add_f32 v[30:31], v[30:31], v[182:183]
	s_waitcnt vmcnt(7)
	v_pk_add_f32 v[32:33], v[32:33], v[184:185]
	v_pk_add_f32 v[34:35], v[34:35], v[186:187]
	s_waitcnt vmcnt(6)
	v_pk_add_f32 v[36:37], v[36:37], v[192:193]
	v_pk_add_f32 v[38:39], v[38:39], v[194:195]
	s_waitcnt vmcnt(5)
	v_pk_add_f32 v[40:41], v[40:41], v[196:197]
	v_pk_add_f32 v[42:43], v[42:43], v[198:199]
	s_waitcnt vmcnt(4)
	v_pk_add_f32 v[44:45], v[44:45], v[200:201]
	v_pk_add_f32 v[46:47], v[46:47], v[202:203]
	s_waitcnt vmcnt(3)
	v_pk_add_f32 v[48:49], v[48:49], v[204:205]
	v_pk_add_f32 v[50:51], v[50:51], v[206:207]
	s_waitcnt vmcnt(2)
	v_pk_add_f32 v[52:53], v[52:53], v[208:209]
	v_pk_add_f32 v[54:55], v[54:55], v[210:211]
	s_waitcnt vmcnt(1)
	v_pk_add_f32 v[56:57], v[56:57], v[212:213]
	v_pk_add_f32 v[58:59], v[58:59], v[214:215]
	s_waitcnt vmcnt(0)
	v_pk_add_f32 v[60:61], v[60:61], v[216:217]
	v_pk_add_f32 v[62:63], v[62:63], v[218:219]
	global_load_dwordx4 v[152:155], v150, s[84:85] sc1
	s_add_u32 s84, s84, s62
	s_addc_u32 s85, s85, 0
	global_load_dwordx4 v[156:159], v150, s[84:85] sc1
	s_add_u32 s84, s84, s62
	s_addc_u32 s85, s85, 0
	global_load_dwordx4 v[160:163], v150, s[84:85] sc1
	s_add_u32 s84, s84, s62
	s_addc_u32 s85, s85, 0
	global_load_dwordx4 v[164:167], v150, s[84:85] sc1
	s_add_u32 s84, s84, s62
	s_addc_u32 s85, s85, 0
	global_load_dwordx4 v[168:171], v150, s[84:85] sc1
	s_add_u32 s84, s84, s62
	s_addc_u32 s85, s85, 0
	global_load_dwordx4 v[172:175], v150, s[84:85] sc1
	s_add_u32 s84, s84, s62
	s_addc_u32 s85, s85, 0
	global_load_dwordx4 v[176:179], v150, s[84:85] sc1
	s_add_u32 s84, s84, s62
	s_addc_u32 s85, s85, 0
	global_load_dwordx4 v[180:183], v150, s[84:85] sc1
	s_add_u32 s84, s84, s62
	s_addc_u32 s85, s85, 0
	global_load_dwordx4 v[184:187], v150, s[84:85] sc1
	s_add_u32 s84, s84, s62
	s_addc_u32 s85, s85, 0
	global_load_dwordx4 v[192:195], v150, s[84:85] sc1
	s_add_u32 s84, s84, s62
	s_addc_u32 s85, s85, 0
	global_load_dwordx4 v[196:199], v150, s[84:85] sc1
	s_add_u32 s84, s84, s62
	s_addc_u32 s85, s85, 0
	global_load_dwordx4 v[200:203], v150, s[84:85] sc1
	s_add_u32 s84, s84, s62
	s_addc_u32 s85, s85, 0
	global_load_dwordx4 v[204:207], v150, s[84:85] sc1
	s_add_u32 s84, s84, s62
	s_addc_u32 s85, s85, 0
	global_load_dwordx4 v[208:211], v150, s[84:85] sc1
	s_add_u32 s84, s84, s62
	s_addc_u32 s85, s85, 0
	global_load_dwordx4 v[212:215], v150, s[84:85] sc1
	s_add_u32 s84, s84, s62
	s_addc_u32 s85, s85, 0
	global_load_dwordx4 v[216:219], v150, s[84:85] sc1
	s_add_u32 s84, s84, s62
	s_addc_u32 s85, s85, 0
	s_waitcnt vmcnt(15)
	v_pk_add_f32 v[64:65], v[64:65], v[152:153]
	v_pk_add_f32 v[66:67], v[66:67], v[154:155]
	s_waitcnt vmcnt(14)
	v_pk_add_f32 v[68:69], v[68:69], v[156:157]
	v_pk_add_f32 v[70:71], v[70:71], v[158:159]
	s_waitcnt vmcnt(13)
	v_pk_add_f32 v[72:73], v[72:73], v[160:161]
	v_pk_add_f32 v[74:75], v[74:75], v[162:163]
	s_waitcnt vmcnt(12)
	v_pk_add_f32 v[76:77], v[76:77], v[164:165]
	v_pk_add_f32 v[78:79], v[78:79], v[166:167]
	s_waitcnt vmcnt(11)
	v_pk_add_f32 v[80:81], v[80:81], v[168:169]
	v_pk_add_f32 v[82:83], v[82:83], v[170:171]
	s_waitcnt vmcnt(10)
	v_pk_add_f32 v[84:85], v[84:85], v[172:173]
	v_pk_add_f32 v[86:87], v[86:87], v[174:175]
	s_waitcnt vmcnt(9)
	v_pk_add_f32 v[88:89], v[88:89], v[176:177]
	v_pk_add_f32 v[90:91], v[90:91], v[178:179]
	s_waitcnt vmcnt(8)
	v_pk_add_f32 v[92:93], v[92:93], v[180:181]
	v_pk_add_f32 v[94:95], v[94:95], v[182:183]
	s_waitcnt vmcnt(7)
	v_pk_add_f32 v[96:97], v[96:97], v[184:185]
	v_pk_add_f32 v[98:99], v[98:99], v[186:187]
	s_waitcnt vmcnt(6)
	v_pk_add_f32 v[100:101], v[100:101], v[192:193]
	v_pk_add_f32 v[102:103], v[102:103], v[194:195]
	s_waitcnt vmcnt(5)
	v_pk_add_f32 v[104:105], v[104:105], v[196:197]
	v_pk_add_f32 v[106:107], v[106:107], v[198:199]
	s_waitcnt vmcnt(4)
	v_pk_add_f32 v[108:109], v[108:109], v[200:201]
	v_pk_add_f32 v[110:111], v[110:111], v[202:203]
	s_waitcnt vmcnt(3)
	v_pk_add_f32 v[112:113], v[112:113], v[204:205]
	v_pk_add_f32 v[114:115], v[114:115], v[206:207]
	s_waitcnt vmcnt(2)
	v_pk_add_f32 v[116:117], v[116:117], v[208:209]
	v_pk_add_f32 v[118:119], v[118:119], v[210:211]
	s_waitcnt vmcnt(1)
	v_pk_add_f32 v[120:121], v[120:121], v[212:213]
	v_pk_add_f32 v[122:123], v[122:123], v[214:215]
	s_waitcnt vmcnt(0)
	v_pk_add_f32 v[124:125], v[124:125], v[216:217]
	v_pk_add_f32 v[126:127], v[126:127], v[218:219]
	global_load_dwordx4 v[152:155], v150, s[84:85] sc1
	s_add_u32 s84, s84, s62
	s_addc_u32 s85, s85, 0
	global_load_dwordx4 v[156:159], v150, s[84:85] sc1
	s_add_u32 s84, s84, s62
	s_addc_u32 s85, s85, 0
	global_load_dwordx4 v[160:163], v150, s[84:85] sc1
	s_add_u32 s84, s84, s62
	s_addc_u32 s85, s85, 0
	global_load_dwordx4 v[164:167], v150, s[84:85] sc1
	s_add_u32 s84, s84, s62
	s_addc_u32 s85, s85, 0
	global_load_dwordx4 v[168:171], v150, s[84:85] sc1
	s_add_u32 s84, s84, s62
	s_addc_u32 s85, s85, 0
	global_load_dwordx4 v[172:175], v150, s[84:85] sc1
	s_add_u32 s84, s84, s62
	s_addc_u32 s85, s85, 0
	global_load_dwordx4 v[176:179], v150, s[84:85] sc1
	s_add_u32 s84, s84, s62
	s_addc_u32 s85, s85, 0
	global_load_dwordx4 v[180:183], v150, s[84:85] sc1
	s_add_u32 s84, s84, s62
	s_addc_u32 s85, s85, 0
	global_load_dwordx4 v[184:187], v150, s[84:85] sc1
	s_add_u32 s84, s84, s62
	s_addc_u32 s85, s85, 0
	global_load_dwordx4 v[192:195], v150, s[84:85] sc1
	s_add_u32 s84, s84, s62
	s_addc_u32 s85, s85, 0
	global_load_dwordx4 v[196:199], v150, s[84:85] sc1
	s_add_u32 s84, s84, s62
	s_addc_u32 s85, s85, 0
	global_load_dwordx4 v[200:203], v150, s[84:85] sc1
	s_add_u32 s84, s84, s62
	s_addc_u32 s85, s85, 0
	global_load_dwordx4 v[204:207], v150, s[84:85] sc1
	s_add_u32 s84, s84, s62
	s_addc_u32 s85, s85, 0
	global_load_dwordx4 v[208:211], v150, s[84:85] sc1
	s_add_u32 s84, s84, s62
	s_addc_u32 s85, s85, 0
	global_load_dwordx4 v[212:215], v150, s[84:85] sc1
	s_add_u32 s84, s84, s62
	s_addc_u32 s85, s85, 0
	global_load_dwordx4 v[216:219], v150, s[84:85] sc1
	s_add_u32 s84, s84, s62
	s_addc_u32 s85, s85, 0
	s_waitcnt vmcnt(15)
	v_pk_add_f32 v[0:1], v[0:1], v[152:153]
	v_pk_add_f32 v[2:3], v[2:3], v[154:155]
	s_waitcnt vmcnt(14)
	v_pk_add_f32 v[4:5], v[4:5], v[156:157]
	v_pk_add_f32 v[6:7], v[6:7], v[158:159]
	s_waitcnt vmcnt(13)
	v_pk_add_f32 v[8:9], v[8:9], v[160:161]
	v_pk_add_f32 v[10:11], v[10:11], v[162:163]
	s_waitcnt vmcnt(12)
	v_pk_add_f32 v[12:13], v[12:13], v[164:165]
	v_pk_add_f32 v[14:15], v[14:15], v[166:167]
	s_waitcnt vmcnt(11)
	v_pk_add_f32 v[16:17], v[16:17], v[168:169]
	v_pk_add_f32 v[18:19], v[18:19], v[170:171]
	s_waitcnt vmcnt(10)
	v_pk_add_f32 v[20:21], v[20:21], v[172:173]
	v_pk_add_f32 v[22:23], v[22:23], v[174:175]
	s_waitcnt vmcnt(9)
	v_pk_add_f32 v[24:25], v[24:25], v[176:177]
	v_pk_add_f32 v[26:27], v[26:27], v[178:179]
	s_waitcnt vmcnt(8)
	v_pk_add_f32 v[28:29], v[28:29], v[180:181]
	v_pk_add_f32 v[30:31], v[30:31], v[182:183]
	s_waitcnt vmcnt(7)
	v_pk_add_f32 v[32:33], v[32:33], v[184:185]
	v_pk_add_f32 v[34:35], v[34:35], v[186:187]
	s_waitcnt vmcnt(6)
	v_pk_add_f32 v[36:37], v[36:37], v[192:193]
	v_pk_add_f32 v[38:39], v[38:39], v[194:195]
	s_waitcnt vmcnt(5)
	v_pk_add_f32 v[40:41], v[40:41], v[196:197]
	v_pk_add_f32 v[42:43], v[42:43], v[198:199]
	s_waitcnt vmcnt(4)
	v_pk_add_f32 v[44:45], v[44:45], v[200:201]
	v_pk_add_f32 v[46:47], v[46:47], v[202:203]
	s_waitcnt vmcnt(3)
	v_pk_add_f32 v[48:49], v[48:49], v[204:205]
	v_pk_add_f32 v[50:51], v[50:51], v[206:207]
	s_waitcnt vmcnt(2)
	v_pk_add_f32 v[52:53], v[52:53], v[208:209]
	v_pk_add_f32 v[54:55], v[54:55], v[210:211]
	s_waitcnt vmcnt(1)
	v_pk_add_f32 v[56:57], v[56:57], v[212:213]
	v_pk_add_f32 v[58:59], v[58:59], v[214:215]
	s_waitcnt vmcnt(0)
	v_pk_add_f32 v[60:61], v[60:61], v[216:217]
	v_pk_add_f32 v[62:63], v[62:63], v[218:219]
	global_load_dwordx4 v[152:155], v150, s[84:85] sc1
	s_add_u32 s84, s84, s62
	s_addc_u32 s85, s85, 0
	global_load_dwordx4 v[156:159], v150, s[84:85] sc1
	s_add_u32 s84, s84, s62
	s_addc_u32 s85, s85, 0
	global_load_dwordx4 v[160:163], v150, s[84:85] sc1
	s_add_u32 s84, s84, s62
	s_addc_u32 s85, s85, 0
	global_load_dwordx4 v[164:167], v150, s[84:85] sc1
	s_add_u32 s84, s84, s62
	s_addc_u32 s85, s85, 0
	global_load_dwordx4 v[168:171], v150, s[84:85] sc1
	s_add_u32 s84, s84, s62
	s_addc_u32 s85, s85, 0
	global_load_dwordx4 v[172:175], v150, s[84:85] sc1
	s_add_u32 s84, s84, s62
	s_addc_u32 s85, s85, 0
	global_load_dwordx4 v[176:179], v150, s[84:85] sc1
	s_add_u32 s84, s84, s62
	s_addc_u32 s85, s85, 0
	global_load_dwordx4 v[180:183], v150, s[84:85] sc1
	s_add_u32 s84, s84, s62
	s_addc_u32 s85, s85, 0
	global_load_dwordx4 v[184:187], v150, s[84:85] sc1
	s_add_u32 s84, s84, s62
	s_addc_u32 s85, s85, 0
	global_load_dwordx4 v[192:195], v150, s[84:85] sc1
	s_add_u32 s84, s84, s62
	s_addc_u32 s85, s85, 0
	global_load_dwordx4 v[196:199], v150, s[84:85] sc1
	s_add_u32 s84, s84, s62
	s_addc_u32 s85, s85, 0
	global_load_dwordx4 v[200:203], v150, s[84:85] sc1
	s_add_u32 s84, s84, s62
	s_addc_u32 s85, s85, 0
	global_load_dwordx4 v[204:207], v150, s[84:85] sc1
	s_add_u32 s84, s84, s62
	s_addc_u32 s85, s85, 0
	global_load_dwordx4 v[208:211], v150, s[84:85] sc1
	s_add_u32 s84, s84, s62
	s_addc_u32 s85, s85, 0
	global_load_dwordx4 v[212:215], v150, s[84:85] sc1
	s_add_u32 s84, s84, s62
	s_addc_u32 s85, s85, 0
	global_load_dwordx4 v[216:219], v150, s[84:85] sc1
	s_add_u32 s84, s84, s62
	s_addc_u32 s85, s85, 0
	s_waitcnt vmcnt(15)
	v_pk_add_f32 v[64:65], v[64:65], v[152:153]
	v_pk_add_f32 v[66:67], v[66:67], v[154:155]
	s_waitcnt vmcnt(14)
	v_pk_add_f32 v[68:69], v[68:69], v[156:157]
	v_pk_add_f32 v[70:71], v[70:71], v[158:159]
	s_waitcnt vmcnt(13)
	v_pk_add_f32 v[72:73], v[72:73], v[160:161]
	v_pk_add_f32 v[74:75], v[74:75], v[162:163]
	s_waitcnt vmcnt(12)
	v_pk_add_f32 v[76:77], v[76:77], v[164:165]
	v_pk_add_f32 v[78:79], v[78:79], v[166:167]
	s_waitcnt vmcnt(11)
	v_pk_add_f32 v[80:81], v[80:81], v[168:169]
	v_pk_add_f32 v[82:83], v[82:83], v[170:171]
	s_waitcnt vmcnt(10)
	v_pk_add_f32 v[84:85], v[84:85], v[172:173]
	v_pk_add_f32 v[86:87], v[86:87], v[174:175]
	s_waitcnt vmcnt(9)
	v_pk_add_f32 v[88:89], v[88:89], v[176:177]
	v_pk_add_f32 v[90:91], v[90:91], v[178:179]
	s_waitcnt vmcnt(8)
	v_pk_add_f32 v[92:93], v[92:93], v[180:181]
	v_pk_add_f32 v[94:95], v[94:95], v[182:183]
	s_waitcnt vmcnt(7)
	v_pk_add_f32 v[96:97], v[96:97], v[184:185]
	v_pk_add_f32 v[98:99], v[98:99], v[186:187]
	s_waitcnt vmcnt(6)
	v_pk_add_f32 v[100:101], v[100:101], v[192:193]
	v_pk_add_f32 v[102:103], v[102:103], v[194:195]
	s_waitcnt vmcnt(5)
	v_pk_add_f32 v[104:105], v[104:105], v[196:197]
	v_pk_add_f32 v[106:107], v[106:107], v[198:199]
	s_waitcnt vmcnt(4)
	v_pk_add_f32 v[108:109], v[108:109], v[200:201]
	v_pk_add_f32 v[110:111], v[110:111], v[202:203]
	s_waitcnt vmcnt(3)
	v_pk_add_f32 v[112:113], v[112:113], v[204:205]
	v_pk_add_f32 v[114:115], v[114:115], v[206:207]
	s_waitcnt vmcnt(2)
	v_pk_add_f32 v[116:117], v[116:117], v[208:209]
	v_pk_add_f32 v[118:119], v[118:119], v[210:211]
	s_waitcnt vmcnt(1)
	v_pk_add_f32 v[120:121], v[120:121], v[212:213]
	v_pk_add_f32 v[122:123], v[122:123], v[214:215]
	s_waitcnt vmcnt(0)
	v_pk_add_f32 v[124:125], v[124:125], v[216:217]
	v_pk_add_f32 v[126:127], v[126:127], v[218:219]
	s_branch .Lsk8_epi

.LBB0_1362:
	s_or_b64 exec, exec, s[2:3]
	s_mov_b64 s[8:9], s[0:1]
	s_waitcnt lgkmcnt(0)
	v_mov_b32_e32 v0, v188
	s_barrier
	s_add_i32 s4, 0, 0x24ffc
	v_mov_b32_e32 v0, s4
	ds_read_b32 v0, v0
	s_movk_i32 s4, 0x13f
	v_mov_b32_e32 v8, v188
	s_waitcnt lgkmcnt(0)
	v_cmp_lt_i32_e32 vcc, s4, v0
	v_readfirstlane_b32 s27, v0
	v_readfirstlane_b32 s16, v8
	s_cbranch_vccnz .Lp16_754
	v_lshlrev_b32_e32 v0, 4, v8
	v_add_u32_e32 v1, 0x2000, v0
	v_ashrrev_i32_e32 v2, 31, v1
	v_lshrrev_b32_e32 v2, 22, v2
	v_add_u32_e32 v2, v1, v2
	v_ashrrev_i32_e32 v9, 10, v2
	v_mul_i32_i24_e32 v2, 0x400, v9
	v_sub_u32_e32 v1, v1, v2
	v_lshrrev_b32_e32 v2, 4, v1
	v_bitop3_b32 v1, v2, v1, 32 bitop3:0x6c
	v_ashrrev_i32_e32 v2, 31, v1
	v_lshrrev_b32_e32 v2, 26, v2
	v_add_u32_e32 v2, v1, v2
	v_lshlrev_b32_e32 v3, 3, v9
	v_ashrrev_i32_e32 v10, 6, v2
	v_and_b32_e32 v3, -16, v3
	v_add_u32_e32 v3, v10, v3
	s_load_dwordx4 s[4:7], s[8:9], 0xa8
	v_and_b32_e32 v4, 3, v10
	s_mov_b32 s8, 0x7ffe0
	v_lshrrev_b32_e32 v5, 2, v3
	v_lshlrev_b32_e32 v6, 1, v3
	v_and_b32_e32 v2, 0xc0, v2
	v_and_or_b32 v4, v3, s8, v4
	v_and_b32_e32 v5, 4, v5
	v_and_b32_e32 v6, 24, v6
	v_sub_u32_e32 v1, v1, v2
	v_mov_b32_e32 v2, 1
	v_or3_b32 v4, v4, v5, v6
	v_lshlrev_b32_e32 v5, 5, v9
	v_ashrrev_i16_sdwa v1, v2, sext(v1) dst_sel:DWORD dst_unused:UNUSED_PAD src0_sel:DWORD src1_sel:BYTE_0
	v_and_b32_e32 v5, 32, v5
	v_bfe_i32 v11, v1, 0, 16
	v_add_lshl_u32 v1, v5, v11, 1
	v_lshl_add_u32 v128, v4, 13, v1
	v_lshl_add_u32 v130, v3, 13, v1
	v_bfe_i32 v1, v8, 27, 1
	v_lshrrev_b32_e32 v1, 22, v1
	v_add_u32_e32 v1, v0, v1
	v_and_b32_e32 v1, 0xfffffc00, v1
	v_sub_u32_e32 v0, v0, v1
	v_lshrrev_b32_e32 v1, 4, v0
	v_ashrrev_i32_e32 v3, 31, v8
	v_bitop3_b32 v0, v1, v0, 32 bitop3:0x6c
	v_lshrrev_b32_e32 v3, 26, v3
	v_ashrrev_i32_e32 v1, 31, v0
	v_add_u32_e32 v3, v8, v3
	v_lshrrev_b32_e32 v1, 26, v1
	v_ashrrev_i32_e32 v13, 6, v3
	v_add_u32_e32 v1, v0, v1
	v_lshlrev_b32_e32 v3, 3, v13
	s_waitcnt lgkmcnt(0)
	s_add_u32 s56, s6, 0xa000000
	v_ashrrev_i32_e32 v12, 6, v1
	v_and_b32_e32 v3, -16, v3
	s_addc_u32 s57, s7, 0
	v_add_u32_e32 v3, v12, v3
	v_and_b32_e32 v4, 3, v12
	s_ashr_i32 s59, s27, 31
	v_and_or_b32 v4, v3, s8, v4
	s_and_b32 s8, s27, 7
	s_lshr_b32 s9, s27, 3
	s_and_b32 s98, s9, 3
	s_lshr_b32 s9, s9, 2
	s_lshl_b32 s99, s8, 3
	s_add_i32 s99, s99, s9
	s_mul_i32 s8, s8, 10
	s_cmp_eq_u32 s98, 3
	s_cbranch_scc1 .Lsk16_q3a
	s_lshr_b32 s10, s9, 2
	s_add_i32 s8, s8, s10
	s_add_i32 s8, s8, 8
	s_and_b32 s9, s9, 3
	s_lshl_b32 s10, s98, 11
	s_movk_i32 s100, 12
	s_branch .Lsk16_q3b

.Lp16_741:
	s_add_u32 s10, s6, 0xc800000
	s_addc_u32 s11, s7, 0
	s_lshl_b32 s5, s5, 5
	s_mov_b64 s[12:13], 0x80
	s_and_b32 s5, s5, 0x60
	s_add_i32 m0, s45, 0x18000
	v_lshl_add_u64 v[6:7], v[6:7], 0, s[12:13]
	s_lshl_b32 s17, s4, 13
	s_lshl_b32 s34, s5, 7
	s_waitcnt vmcnt(2)
	s_barrier
	global_load_lds_dwordx4 v[6:7], off
	v_lshl_add_u64 v[4:5], v[4:5], 0, s[12:13]
	s_add_i32 m0, s45, 0x1a000
	s_add_i32 s66, s45, 0x8000
	s_add_i32 s67, s45, 0xa000
	global_load_lds_dwordx4 v[4:5], off
	v_lshl_add_u64 v[0:1], v[0:1], 0, s[12:13]
	s_mov_b32 m0, s66
	s_add_u32 s18, s52, 0x100080
	global_load_lds_dwordx4 v[0:1], off
	v_lshl_add_u64 v[0:1], v[2:3], 0, s[12:13]
	s_mov_b32 m0, s67
	s_addc_u32 s19, s53, 0
	global_load_lds_dwordx4 v[0:1], off
	s_add_i32 m0, s45, 0x1c000
	v_lshl_add_u64 v[0:1], s[18:19], 0, v[132:133]
	global_load_lds_dwordx4 v[0:1], off
	v_lshl_add_u64 v[0:1], s[18:19], 0, v[128:129]
	s_add_i32 m0, s45, 0x1e000
	s_cmpk_lt_u32 s16, 0x100
	global_load_lds_dwordx4 v[0:1], off
	v_lshrrev_b32_e32 v1, 1, v8
	v_and_b32_e32 v1, 24, v1
	v_and_b32_e32 v0, 15, v8
	v_lshlrev_b32_e32 v2, 1, v1
	v_lshl_or_b32 v144, s4, 6, v0
	v_lshl_or_b32 v0, v0, 6, v2
	v_lshlrev_b32_e32 v2, 2, v8
	v_and_b32_e32 v2, 32, v2
	v_bitop3_b32 v3, v0, s17, v2 bitop3:0xde
	v_bitop3_b32 v145, v0, s34, v2 bitop3:0xde
	v_lshlrev_b32_e32 v0, 16, v13
	v_and_b32_e32 v0, 0xfffe0000, v0
	v_or_b32_e32 v146, s5, v1
	v_lshl_add_u32 v0, v12, 13, v0
	v_and_b32_e32 v1, 1, v13
	v_lshl_or_b32 v0, v1, 6, v0
	v_lshl_add_u32 v136, v14, 1, v0
	v_lshlrev_b32_e32 v0, 16, v9
	v_and_b32_e32 v0, 0xfffe0000, v0
	s_waitcnt vmcnt(6)
	v_lshl_add_u32 v0, v10, 13, v0
	v_and_b32_e32 v1, 1, v9
	s_cselect_b64 s[16:17], -1, 0
	v_lshl_or_b32 v0, v1, 6, v0
	s_add_i32 s71, 0, 0x10000
	s_add_i32 s72, 0, 0x14000
	s_mov_b32 s68, 0
	s_ashr_i32 s69, s22, 31
	s_mov_b32 s70, s22
	v_mov_b32_e32 v137, v133
	v_lshl_add_u32 v138, v11, 1, v0
	v_mov_b32_e32 v139, v133
	v_mov_b64_e32 v[140:141], 0x140
	v_mov_b64_e32 v[142:143], 0x13f
	v_add_u32_e32 v147, s71, v145
	v_add_u32_e32 v148, s72, v145
	v_add_u32_e32 v149, 0, v3
	s_mov_b64 s[18:19], 0x40000
	s_mov_b32 s73, 0x40000
	s_mov_b64 s[34:35], 0x48000
	s_mov_b32 s74, 0x48000
	s_mov_b64 s[36:37], 0x50000
	s_mov_b32 s75, 0x50000
	s_mov_b64 s[38:39], 0x58000
	s_mov_b32 s76, 0x58000
	s_barrier
	s_branch .Lp16_744

.Lsk16_pstore:
	s_mul_i32 s54, s99, 3
	s_add_i32 s54, s54, s98
	s_lshl_b32 s55, s54, 2
	s_mov_b32 s62, 0x2000
	s_movk_i32 s80, 0x800
	s_cmp_lt_u32 s99, 42
	s_cbranch_scc1 .Lsk16_sa_a1
	s_cmp_lt_u32 s99, 60
	s_cbranch_scc1 .Lsk16_sa_b1
	s_cmp_eq_u32 s99, 60
	s_cbranch_scc1 .Lsk16_sa_c1
	s_load_dwordx2 s[84:85], s[0:1], 0xa8
	s_add_i32 s54, s99, -61
	s_mul_i32 s54, s54, 0x180000
	s_waitcnt lgkmcnt(0)
	s_add_u32 s84, s84, s54
	s_addc_u32 s85, s85, 0
	s_mov_b32 s62, 0x4000
	s_movk_i32 s80, 0x1000
	s_mul_i32 s64, s98, 0x80000
	s_branch .Lsk16_sa_j1
.Lsk16_sa_a1:
	s_mul_i32 s54, s99, 0xc0000
	s_add_u32 s84, s6, 0xa800000
	s_addc_u32 s85, s7, 0
	s_add_u32 s84, s84, s54
	s_addc_u32 s85, s85, 0
	s_mul_i32 s64, s98, 0x40000
	s_branch .Lsk16_sa_j1
.Lsk16_sa_b1:
	s_add_i32 s54, s99, -42
	s_mul_i32 s54, s54, 0xc0000
	s_add_u32 s84, s6, 0xf000000
	s_addc_u32 s85, s7, 0
	s_add_u32 s84, s84, s54
	s_addc_u32 s85, s85, 0
	s_mul_i32 s64, s98, 0x40000
	s_branch .Lsk16_sa_j1
.Lsk16_sa_c1:
	s_add_u32 s84, s6, 0xff04000
	s_addc_u32 s85, s7, 0
	s_mul_i32 s64, s98, 0x40000
.Lsk16_sa_j1:
	s_add_u32 s84, s84, s64
	s_addc_u32 s85, s85, 0
	v_lshrrev_b32_e32 v150, 7, v188
	v_mul_lo_u32 v150, v150, s80
	v_and_b32_e32 v151, 0x7f, v188
	v_lshl_add_u32 v150, v151, 4, v150
	global_store_dwordx4 v150, v[0:3], s[84:85] sc1
	s_add_u32 s84, s84, s62
	s_addc_u32 s85, s85, 0
	global_store_dwordx4 v150, v[4:7], s[84:85] sc1
	s_add_u32 s84, s84, s62
	s_addc_u32 s85, s85, 0
	global_store_dwordx4 v150, v[8:11], s[84:85] sc1
	s_add_u32 s84, s84, s62
	s_addc_u32 s85, s85, 0
	global_store_dwordx4 v150, v[12:15], s[84:85] sc1
	s_add_u32 s84, s84, s62
	s_addc_u32 s85, s85, 0
	global_store_dwordx4 v150, v[16:19], s[84:85] sc1
	s_add_u32 s84, s84, s62
	s_addc_u32 s85, s85, 0
	global_store_dwordx4 v150, v[20:23], s[84:85] sc1
	s_add_u32 s84, s84, s62
	s_addc_u32 s85, s85, 0
	global_store_dwordx4 v150, v[24:27], s[84:85] sc1
	s_add_u32 s84, s84, s62
	s_addc_u32 s85, s85, 0
	global_store_dwordx4 v150, v[28:31], s[84:85] sc1
	s_add_u32 s84, s84, s62
	s_addc_u32 s85, s85, 0
	global_store_dwordx4 v150, v[32:35], s[84:85] sc1
	s_add_u32 s84, s84, s62
	s_addc_u32 s85, s85, 0
	global_store_dwordx4 v150, v[36:39], s[84:85] sc1
	s_add_u32 s84, s84, s62
	s_addc_u32 s85, s85, 0
	global_store_dwordx4 v150, v[40:43], s[84:85] sc1
	s_add_u32 s84, s84, s62
	s_addc_u32 s85, s85, 0
	global_store_dwordx4 v150, v[44:47], s[84:85] sc1
	s_add_u32 s84, s84, s62
	s_addc_u32 s85, s85, 0
	global_store_dwordx4 v150, v[48:51], s[84:85] sc1
	s_add_u32 s84, s84, s62
	s_addc_u32 s85, s85, 0
	global_store_dwordx4 v150, v[52:55], s[84:85] sc1
	s_add_u32 s84, s84, s62
	s_addc_u32 s85, s85, 0
	global_store_dwordx4 v150, v[56:59], s[84:85] sc1
	s_add_u32 s84, s84, s62
	s_addc_u32 s85, s85, 0
	global_store_dwordx4 v150, v[60:63], s[84:85] sc1
	s_add_u32 s84, s84, s62
	s_addc_u32 s85, s85, 0
	global_store_dwordx4 v150, v[64:67], s[84:85] sc1
	s_add_u32 s84, s84, s62
	s_addc_u32 s85, s85, 0
	global_store_dwordx4 v150, v[68:71], s[84:85] sc1
	s_add_u32 s84, s84, s62
	s_addc_u32 s85, s85, 0
	global_store_dwordx4 v150, v[72:75], s[84:85] sc1
	s_add_u32 s84, s84, s62
	s_addc_u32 s85, s85, 0
	global_store_dwordx4 v150, v[76:79], s[84:85] sc1
	s_add_u32 s84, s84, s62
	s_addc_u32 s85, s85, 0
	global_store_dwordx4 v150, v[80:83], s[84:85] sc1
	s_add_u32 s84, s84, s62
	s_addc_u32 s85, s85, 0
	global_store_dwordx4 v150, v[84:87], s[84:85] sc1
	s_add_u32 s84, s84, s62
	s_addc_u32 s85, s85, 0
	global_store_dwordx4 v150, v[88:91], s[84:85] sc1
	s_add_u32 s84, s84, s62
	s_addc_u32 s85, s85, 0
	global_store_dwordx4 v150, v[92:95], s[84:85] sc1
	s_add_u32 s84, s84, s62
	s_addc_u32 s85, s85, 0
	global_store_dwordx4 v150, v[96:99], s[84:85] sc1
	s_add_u32 s84, s84, s62
	s_addc_u32 s85, s85, 0
	global_store_dwordx4 v150, v[100:103], s[84:85] sc1
	s_add_u32 s84, s84, s62
	s_addc_u32 s85, s85, 0
	global_store_dwordx4 v150, v[104:107], s[84:85] sc1
	s_add_u32 s84, s84, s62
	s_addc_u32 s85, s85, 0
	global_store_dwordx4 v150, v[108:111], s[84:85] sc1
	s_add_u32 s84, s84, s62
	s_addc_u32 s85, s85, 0
	global_store_dwordx4 v150, v[112:115], s[84:85] sc1
	s_add_u32 s84, s84, s62
	s_addc_u32 s85, s85, 0
	global_store_dwordx4 v150, v[116:119], s[84:85] sc1
	s_add_u32 s84, s84, s62
	s_addc_u32 s85, s85, 0
	global_store_dwordx4 v150, v[120:123], s[84:85] sc1
	s_add_u32 s84, s84, s62
	s_addc_u32 s85, s85, 0
	global_store_dwordx4 v150, v[124:127], s[84:85] sc1
	s_waitcnt vmcnt(0)
	s_barrier
	s_and_saveexec_b64 s[80:81], s[14:15]
	s_cbranch_execz .Lsk16_pdone
	v_mov_b32_e32 v151, 1
	v_mov_b32_e32 v152, s55
	v_add_u32_e32 v152, 0x3900, v152
	global_store_dword v152, v151, s[24:25] sc1

.Lsk16_rload:
	s_mul_i32 s54, s99, 3
	s_lshl_b32 s55, s54, 2
	s_mov_b32 s62, 0x2000
	s_movk_i32 s80, 0x800
	s_cmp_lt_u32 s99, 42
	s_cbranch_scc1 .Lsk16_sa_a0
	s_cmp_lt_u32 s99, 60
	s_cbranch_scc1 .Lsk16_sa_b0
	s_cmp_eq_u32 s99, 60
	s_cbranch_scc1 .Lsk16_sa_c0
	s_load_dwordx2 s[84:85], s[0:1], 0xa8
	s_add_i32 s54, s99, -61
	s_mul_i32 s54, s54, 0x180000
	s_waitcnt lgkmcnt(0)
	s_add_u32 s84, s84, s54
	s_addc_u32 s85, s85, 0
	s_mov_b32 s62, 0x4000
	s_movk_i32 s80, 0x1000
	s_mov_b32 s64, 0
	s_branch .Lsk16_sa_j0
.Lsk16_sa_a0:
	s_mul_i32 s54, s99, 0xc0000
	s_add_u32 s84, s6, 0xa800000
	s_addc_u32 s85, s7, 0
	s_add_u32 s84, s84, s54
	s_addc_u32 s85, s85, 0
	s_mov_b32 s64, 0
	s_branch .Lsk16_sa_j0
.Lsk16_sa_b0:
	s_add_i32 s54, s99, -42
	s_mul_i32 s54, s54, 0xc0000
	s_add_u32 s84, s6, 0xf000000
	s_addc_u32 s85, s7, 0
	s_add_u32 s84, s84, s54
	s_addc_u32 s85, s85, 0
	s_mov_b32 s64, 0
	s_branch .Lsk16_sa_j0
.Lsk16_sa_c0:
	s_add_u32 s84, s6, 0xff04000
	s_addc_u32 s85, s7, 0
	s_mov_b32 s64, 0
.Lsk16_sa_j0:
	s_add_u32 s84, s84, s64
	s_addc_u32 s85, s85, 0
	v_lshrrev_b32_e32 v150, 7, v188
	v_mul_lo_u32 v150, v150, s80
	v_and_b32_e32 v151, 0x7f, v188
	v_lshl_add_u32 v150, v151, 4, v150
	s_and_saveexec_b64 s[80:81], s[14:15]
	s_cbranch_execz .Lsk16_polled
	v_mov_b32_e32 v152, s55
	v_add_u32_e32 v152, 0x3900, v152
	s_mov_b32 s64, 0
